# speedup vs baseline: 1.0034x; 1.0034x over previous
; __device__ __forceinline__ void phase_norm1(const Params& p, int wid_s) {
;     ...
;   for (int job = blockIdx.x; job < NTOK / 8; job += gridDim.x) {
;     int tok = job * 8 + wid;
;     const float* xr = xrow(p, tok);
;     const float* ad = ada + batch_of(tok) * 12288;
;     float4 xv[8];
;     float ss = 0.f;
; #pragma unroll
;     for (int i = 0; i < 8; ++i) {
;       xv[i] = *(const float4*)(xr + i * 256 + lane * 4);
;       ss += xv[i].x * xv[i].x + xv[i].y * xv[i].y + xv[i].z * xv[i].z + xv[i].w * xv[i].w;
;     }
;     ss = red64(ss);
;     float rs = rsqrtf(ss * (1.f / 2048.f) + 1e-6f);
; #pragma unroll
;     for (int i = 0; i < 8; ++i) {
;       int c = i * 256 + lane * 4;
;       float4 g = *(const float4*)(p.ln_mix_pre + c);
;       float4 sh = *(const float4*)(ad + c);
;       float4 sc = *(const float4*)(ad + 2048 + c);
.LBB0_144:
	s_add_i32 s4, s0, 0xffffe000
	s_lshr_b32 s5, s4, 12
	s_ashr_i32 s1, s0, 31
	s_lshr_b32 s6, s0, 11
	s_add_i32 s7, s5, 4
	s_cmpk_lt_i32 s0, 0x2000
	s_cselect_b32 s5, s1, 0
	s_cselect_b32 s4, s0, s4
	s_cselect_b32 s12, s37, s39
	s_cselect_b32 s13, s36, s38
	s_cselect_b32 s6, s6, s7
	s_lshl_b64 s[4:5], s[4:5], 13
	s_add_u32 s4, s13, s4
	s_addc_u32 s5, s12, s5
	v_lshl_add_u64 v[0:1], s[4:5], 0, v[12:13]
	global_load_dwordx4 v[38:41], v[14:15], off
	global_load_dwordx4 v[42:45], v12, s[4:5]
	global_load_dwordx4 v[46:49], v12, s[4:5] offset:1024
	v_add_co_u32_e32 v0, vcc, s9, v0
	global_load_dwordx4 v[50:53], v12, s[4:5] offset:2048
	global_load_dwordx4 v[54:57], v12, s[4:5] offset:3072
	v_addc_co_u32_e32 v1, vcc, 0, v1, vcc
	global_load_dwordx4 v[58:61], v[0:1], off
	global_load_dwordx4 v[8:11], v[0:1], off offset:1024
	global_load_dwordx4 v[4:7], v[0:1], off offset:2048
	s_nop 0
	global_load_dwordx4 v[0:3], v[0:1], off offset:3072
	s_mulk_i32 s6, 0x3000
	s_ashr_i32 s7, s6, 31
	s_lshl_b64 s[6:7], s[6:7], 2
	s_add_u32 s4, s2, s6
	s_addc_u32 s5, s3, s7
	s_add_u32 s6, s4, 0x2000
	s_addc_u32 s7, s5, 0
	global_load_dwordx4 v[62:65], v12, s[4:5]
	global_load_dwordx4 v[66:69], v12, s[6:7]
	global_load_dwordx4 v[100:103], v[14:15], off offset:1024
	global_load_dwordx4 v[104:107], v30, s[6:7]
	global_load_dwordx4 v[108:111], v12, s[4:5] offset:1024
	global_load_dwordx4 v[112:115], v[14:15], off offset:2048
	global_load_dwordx4 v[116:119], v31, s[6:7]
	global_load_dwordx4 v[120:123], v12, s[4:5] offset:2048
	global_load_dwordx4 v[124:127], v[14:15], off offset:3072
	global_load_dwordx4 v[128:131], v32, s[6:7]
	global_load_dwordx4 v[132:135], v12, s[4:5] offset:3072
	global_load_dwordx4 v[136:139], v[16:17], off
	global_load_dwordx4 v[140:143], v33, s[6:7]
	global_load_dwordx4 v[144:147], v33, s[4:5]
	global_load_dwordx4 v[148:151], v[18:19], off
	global_load_dwordx4 v[152:155], v34, s[6:7]
	global_load_dwordx4 v[156:159], v34, s[4:5]
	global_load_dwordx4 v[160:163], v[20:21], off
	global_load_dwordx4 v[164:167], v35, s[6:7]
	global_load_dwordx4 v[168:171], v35, s[4:5]
	global_load_dwordx4 v[172:175], v[22:23], off
	global_load_dwordx4 v[176:179], v36, s[6:7]
	global_load_dwordx4 v[180:183], v36, s[4:5]
	s_lshl_b64 s[12:13], s[0:1], 12
	v_lshl_add_u64 v[26:27], v[24:25], 0, s[12:13]
	s_add_i32 s11, s11, s33
	s_add_i32 s0, s0, s8
	s_cmpk_lt_i32 s11, 0x1400
	s_waitcnt vmcnt(30)
	v_pk_mul_f32 v[72:73], v[42:43], v[42:43]
	s_waitcnt vmcnt(29)
	v_pk_mul_f32 v[76:77], v[46:47], v[46:47]
	v_pk_mul_f32 v[70:71], v[44:45], v[44:45]
	v_pk_mul_f32 v[74:75], v[48:49], v[48:49]
	s_waitcnt vmcnt(28)
	v_pk_mul_f32 v[80:81], v[50:51], v[50:51]
	s_waitcnt vmcnt(27)
	v_pk_mul_f32 v[84:85], v[54:55], v[54:55]
	v_add_f32_e32 v94, v76, v77
	v_add_f32_e32 v95, v72, v73
	v_pk_mul_f32 v[78:79], v[52:53], v[52:53]
	v_add_f32_e32 v96, v80, v81
	v_add_f32_e32 v97, v84, v85
	s_waitcnt vmcnt(26)
	v_mov_b32_e32 v84, v59
	s_waitcnt vmcnt(25)
	v_mov_b32_e32 v85, v9
	s_waitcnt vmcnt(24)
	v_mov_b32_e32 v92, v5
	s_waitcnt vmcnt(23)
	v_mov_b32_e32 v93, v1
	v_add_f32_e32 v74, v94, v74
	v_add_f32_e32 v70, v95, v70
	v_pk_mul_f32 v[82:83], v[56:57], v[56:57]
	v_mov_b32_e32 v80, v58
	v_mov_b32_e32 v81, v8
	v_mov_b32_e32 v90, v4
	v_mov_b32_e32 v91, v0
	v_add_f32_e32 v78, v96, v78
	v_pk_mul_f32 v[84:85], v[84:85], v[84:85]
	v_pk_mul_f32 v[92:93], v[92:93], v[92:93]
	v_add_f32_e32 v94, v74, v75
	v_add_f32_e32 v95, v70, v71
	v_mov_b32_e32 v72, v60
	v_mov_b32_e32 v73, v10
	v_mov_b32_e32 v86, v6
	v_mov_b32_e32 v87, v2
	v_add_f32_e32 v82, v97, v82
	v_add_f32_e32 v78, v78, v79
	v_pk_fma_f32 v[70:71], v[80:81], v[80:81], v[84:85]
	v_pk_fma_f32 v[74:75], v[90:91], v[90:91], v[92:93]
	v_add_f32_e32 v80, v95, v94
	v_mov_b32_e32 v76, v61
	v_mov_b32_e32 v77, v11
	v_add_f32_e32 v79, v82, v83
	v_pk_fma_f32 v[70:71], v[72:73], v[72:73], v[70:71]
	v_pk_fma_f32 v[72:73], v[86:87], v[86:87], v[74:75]
	v_add_f32_e32 v74, v80, v78
	v_pk_fma_f32 v[70:71], v[76:77], v[76:77], v[70:71]
	v_add_f32_e32 v74, v74, v79
	v_mov_b32_e32 v88, v7
	v_mov_b32_e32 v89, v3
	v_add_f32_e32 v70, v74, v70
	v_pk_fma_f32 v[72:73], v[88:89], v[88:89], v[72:73]
	v_add_f32_e32 v70, v70, v71
	v_add_f32_e32 v70, v70, v72
	v_add_f32_e32 v70, v70, v73
	s_waitcnt vmcnt(0)
	v_pk_add_f32 v[66:67], v[66:67], 1.0 op_sel_hi:[1,0]
	v_pk_add_f32 v[68:69], v[68:69], 1.0 op_sel_hi:[1,0]
	v_add_f32_dpp v70, v70, v70 quad_perm:[1,0,3,2] row_mask:0xf bank_mask:0xf bound_ctrl:1
	s_nop 1
	v_add_f32_dpp v70, v70, v70 quad_perm:[2,3,0,1] row_mask:0xf bank_mask:0xf bound_ctrl:1
	s_nop 1
	v_add_f32_dpp v70, v70, v70 row_half_mirror row_mask:0xf bank_mask:0xf bound_ctrl:1
	s_nop 1
	v_add_f32_dpp v70, v70, v70 row_mirror row_mask:0xf bank_mask:0xf bound_ctrl:1
	ds_bpermute_b32 v71, v28, v70
	s_waitcnt lgkmcnt(0)
; __device__ __forceinline__ void phase_norm1(const Params& p, int wid_s) {
;     ...
;     ss = red64(ss);
;     float rs = rsqrtf(ss * (1.f / 2048.f) + 1e-6f);
; #pragma unroll
;     for (int i = 0; i < 8; ++i) {
;       int c = i * 256 + lane * 4;
;       float4 g = *(const float4*)(p.ln_mix_pre + c);
;       float4 sh = *(const float4*)(ad + c);
;       float4 sc = *(const float4*)(ad + 2048 + c);
;       uint2 o;
;       o.x = pack2(xv[i].x * rs * g.x * (1.f + sc.x) + sh.x, xv[i].y * rs * g.y * (1.f + sc.y) + sh.y);
;       o.y = pack2(xv[i].z * rs * g.z * (1.f + sc.z) + sh.z, xv[i].w * rs * g.w * (1.f + sc.w) + sh.w);
;       *(uint2*)(H + (size_t)tok * 2048 + c) = o;
;     }
	v_add_f32_e32 v70, v70, v71
	ds_bpermute_b32 v71, v29, v70
	s_waitcnt lgkmcnt(0)
	v_add_f32_e32 v70, v70, v71
	v_fmamk_f32 v70, v70, 0x3a000000, v37
	v_mul_f32_e32 v71, 0x4b800000, v70
	v_cmp_gt_f32_e32 vcc, s10, v70
	s_nop 1
	v_cndmask_b32_e32 v70, v70, v71, vcc
	v_rsq_f32_e32 v70, v70
	s_nop 0
	v_mul_f32_e32 v71, 0x45800000, v70
	v_cndmask_b32_e32 v70, v70, v71, vcc
	v_pk_mul_f32 v[42:43], v[42:43], v[70:71] op_sel_hi:[1,0]
	v_pk_mul_f32 v[44:45], v[44:45], v[70:71] op_sel_hi:[1,0]
	v_pk_mul_f32 v[38:39], v[38:39], v[42:43]
	v_pk_mul_f32 v[40:41], v[40:41], v[44:45]
	v_pk_fma_f32 v[38:39], v[66:67], v[38:39], v[62:63]
	v_pk_fma_f32 v[40:41], v[68:69], v[40:41], v[64:65]
	v_cvt_pk_bf16_f32 v38, v38, v39
	v_cvt_pk_bf16_f32 v39, v40, v41
	global_store_dwordx2 v[26:27], v[38:39], off
	s_nop 0
	v_pk_mul_f32 v[46:47], v[46:47], v[70:71] op_sel_hi:[1,0]
	v_pk_mul_f32 v[48:49], v[48:49], v[70:71] op_sel_hi:[1,0]
	v_pk_mul_f32 v[50:51], v[50:51], v[70:71] op_sel_hi:[1,0]
	v_pk_mul_f32 v[52:53], v[52:53], v[70:71] op_sel_hi:[1,0]
	v_pk_mul_f32 v[8:9], v[8:9], v[70:71] op_sel_hi:[1,0]
	v_pk_mul_f32 v[10:11], v[10:11], v[70:71] op_sel_hi:[1,0]
	v_pk_mul_f32 v[4:5], v[4:5], v[70:71] op_sel_hi:[1,0]
	v_pk_mul_f32 v[6:7], v[6:7], v[70:71] op_sel_hi:[1,0]
	v_pk_mul_f32 v[0:1], v[0:1], v[70:71] op_sel_hi:[1,0]
	v_pk_mul_f32 v[2:3], v[2:3], v[70:71] op_sel_hi:[1,0]
	v_pk_mul_f32 v[38:39], v[46:47], v[100:101]
	v_pk_add_f32 v[42:43], v[104:105], 1.0 op_sel_hi:[1,0]
	v_pk_mul_f32 v[40:41], v[48:49], v[102:103]
	v_pk_add_f32 v[44:45], v[106:107], 1.0 op_sel_hi:[1,0]
	v_pk_fma_f32 v[38:39], v[38:39], v[42:43], v[108:109]
	v_pk_fma_f32 v[40:41], v[40:41], v[44:45], v[110:111]
	v_cvt_pk_bf16_f32 v38, v38, v39
	v_cvt_pk_bf16_f32 v39, v40, v41
	global_store_dwordx2 v[26:27], v[38:39], off offset:512
	s_nop 0
	v_pk_mul_f32 v[38:39], v[50:51], v[112:113]
	v_pk_add_f32 v[42:43], v[116:117], 1.0 op_sel_hi:[1,0]
	v_pk_mul_f32 v[40:41], v[52:53], v[114:115]
	v_pk_add_f32 v[44:45], v[118:119], 1.0 op_sel_hi:[1,0]
	v_pk_fma_f32 v[38:39], v[38:39], v[42:43], v[120:121]
	v_pk_fma_f32 v[40:41], v[40:41], v[44:45], v[122:123]
	v_cvt_pk_bf16_f32 v38, v38, v39
	v_cvt_pk_bf16_f32 v39, v40, v41
	global_store_dwordx2 v[26:27], v[38:39], off offset:1024
	s_nop 0
	v_pk_mul_f32 v[50:51], v[54:55], v[70:71] op_sel_hi:[1,0]
	v_pk_mul_f32 v[52:53], v[56:57], v[70:71] op_sel_hi:[1,0]
	v_pk_mul_f32 v[38:39], v[50:51], v[124:125]
	v_pk_add_f32 v[42:43], v[128:129], 1.0 op_sel_hi:[1,0]
	v_pk_mul_f32 v[40:41], v[52:53], v[126:127]
	v_pk_add_f32 v[44:45], v[130:131], 1.0 op_sel_hi:[1,0]
	v_pk_fma_f32 v[38:39], v[38:39], v[42:43], v[132:133]
	v_pk_fma_f32 v[40:41], v[40:41], v[44:45], v[134:135]
	v_cvt_pk_bf16_f32 v38, v38, v39
	v_cvt_pk_bf16_f32 v39, v40, v41
	global_store_dwordx2 v[26:27], v[38:39], off offset:1536
	s_nop 0
	v_pk_mul_f32 v[50:51], v[58:59], v[70:71] op_sel_hi:[1,0]
	v_pk_mul_f32 v[52:53], v[60:61], v[70:71] op_sel_hi:[1,0]
	v_pk_mul_f32 v[38:39], v[50:51], v[136:137]
	v_pk_add_f32 v[42:43], v[140:141], 1.0 op_sel_hi:[1,0]
	v_pk_mul_f32 v[40:41], v[52:53], v[138:139]
	v_pk_add_f32 v[44:45], v[142:143], 1.0 op_sel_hi:[1,0]
	v_pk_fma_f32 v[38:39], v[38:39], v[42:43], v[144:145]
	v_pk_fma_f32 v[40:41], v[40:41], v[44:45], v[146:147]
	v_cvt_pk_bf16_f32 v38, v38, v39
	v_cvt_pk_bf16_f32 v39, v40, v41
	global_store_dwordx2 v[26:27], v[38:39], off offset:2048
	s_nop 0
	v_pk_mul_f32 v[8:9], v[8:9], v[148:149]
	v_pk_add_f32 v[38:39], v[152:153], 1.0 op_sel_hi:[1,0]
	v_pk_mul_f32 v[10:11], v[10:11], v[150:151]
	v_pk_add_f32 v[40:41], v[154:155], 1.0 op_sel_hi:[1,0]
	v_pk_fma_f32 v[8:9], v[8:9], v[38:39], v[156:157]
	v_pk_fma_f32 v[10:11], v[10:11], v[40:41], v[158:159]
	v_cvt_pk_bf16_f32 v8, v8, v9
	v_cvt_pk_bf16_f32 v9, v10, v11
	global_store_dwordx2 v[26:27], v[8:9], off offset:2560
	s_nop 0
	v_pk_mul_f32 v[4:5], v[4:5], v[160:161]
	v_pk_add_f32 v[8:9], v[164:165], 1.0 op_sel_hi:[1,0]
	v_pk_mul_f32 v[6:7], v[6:7], v[162:163]
	v_pk_add_f32 v[10:11], v[166:167], 1.0 op_sel_hi:[1,0]
	v_pk_fma_f32 v[4:5], v[4:5], v[8:9], v[168:169]
	v_pk_fma_f32 v[6:7], v[6:7], v[10:11], v[170:171]
	v_cvt_pk_bf16_f32 v4, v4, v5
	v_cvt_pk_bf16_f32 v5, v6, v7
	global_store_dwordx2 v[26:27], v[4:5], off offset:3072
	s_nop 0
	v_pk_mul_f32 v[0:1], v[0:1], v[172:173]
	v_pk_add_f32 v[4:5], v[176:177], 1.0 op_sel_hi:[1,0]
	v_pk_mul_f32 v[2:3], v[2:3], v[174:175]
	v_pk_add_f32 v[6:7], v[178:179], 1.0 op_sel_hi:[1,0]
	v_pk_fma_f32 v[0:1], v[0:1], v[4:5], v[180:181]
	v_pk_fma_f32 v[2:3], v[2:3], v[6:7], v[182:183]
	v_cvt_pk_bf16_f32 v0, v0, v1
	v_cvt_pk_bf16_f32 v1, v2, v3
	global_store_dwordx2 v[26:27], v[0:1], off offset:3584
	s_cbranch_scc1 .LBB0_144

; __device__ __forceinline__ void phase_scan(const Params& p, int wid_s, char* shm) {
;     ...
;       if (ch < mynch) {
;         const float* cb = buf + (ch & 1) * BUF_F + cg8 * 8;
;         const float* cv = buf + (ch & 1) * BUF_F + 320 + rg * 2;
;         const float* ck = buf + (ch & 1) * BUF_F + 384;
;         float* yw = ybuf + (ch & 1) * (SCAN_CH * 64) + rg * 2;
; #pragma unroll 8
;         for (int s = 0; s < SCAN_CH; ++s) {
;           const float* rec = cb + s * SCAN_STEP_F;
;           v2f kk[4], wr8[4], w8[4], ka8[4], kd8[4];
; #pragma unroll
;           for (int c = 0; c < 4; ++c) {
;             kk[c] = *(const v2f*)(rec + 0 + c * 2);
;             wr8[c] = *(const v2f*)(rec + 64 + c * 2);
;             w8[c] = *(const v2f*)(rec + 128 + c * 2);
;             ka8[c] = *(const v2f*)(rec + 192 + c * 2);
;             kd8[c] = *(const v2f*)(rec + 256 + c * 2);
;           }
;           v2f vv = *(const v2f*)(cv + s * SCAN_STEP_F);
;           v2f krdr = *(const v2f*)(ck + s * SCAN_STEP_F);
.LBB0_864:
	s_or_b64 exec, exec, s[40:41]
	v_cmp_lt_u32_e32 vcc, s64, v121
	s_and_saveexec_b64 s[40:41], vcc
	s_cbranch_execz .LBB0_867
	v_cndmask_b32_e64 v2, 0, 1, s[26:27]
	v_mul_lo_u32 v3, v2, s45
	v_add_u32_e32 v0, v114, v3
	v_add_u32_e32 v62, v115, v3
	v_add_u32_e32 v64, v116, v3
	v_lshl_add_u32 v79, v2, 12, v117
	s_mov_b32 s42, 16
	ds_read_b128 v[160:163], v0 offset:0
	ds_read_b128 v[164:167], v0 offset:16
	ds_read_b128 v[168:171], v0 offset:256
	ds_read_b128 v[172:175], v0 offset:272
	ds_read_b128 v[176:179], v0 offset:512
	ds_read_b128 v[180:183], v0 offset:528
	ds_read_b128 v[184:187], v0 offset:768
	ds_read_b128 v[188:191], v0 offset:784
	ds_read_b128 v[192:195], v0 offset:1024
	ds_read_b128 v[196:199], v0 offset:1040
	ds_read_b64 v[200:201], v62 offset:0
	ds_read_b64 v[202:203], v64 offset:0

; __device__ __forceinline__ float bflo(unsigned u) { return __uint_as_float(u << 16); }
; __device__ __forceinline__ float bfhi(unsigned u) { return __uint_as_float(u & 0xffff0000u); }
; __device__ __forceinline__ void phase_norm2(const Params& p, int wid_s) {
;     ...
;   for (int job = blockIdx.x; job < NTOK / 8; job += gridDim.x) {
;     int tok = job * 8 + wid;
;     const float* xr = xrow(p, tok);
;     const float* ad = ada + batch_of(tok) * 12288;
;     float mv[8][4];
;     float ss = 0.f;
; #pragma unroll
;     for (int i = 0; i < 8; ++i) {
;       uint2 u = *(const uint2*)(MIX + (size_t)tok * 2048 + i * 256 + lane * 4);
;       mv[i][0] = bflo(u.x); mv[i][1] = bfhi(u.x); mv[i][2] = bflo(u.y); mv[i][3] = bfhi(u.y);
;       ss += mv[i][0] * mv[i][0] + mv[i][1] * mv[i][1] + mv[i][2] * mv[i][2] + mv[i][3] * mv[i][3];
;     }
;     ss = red64(ss);
.LBB0_1020:
	s_add_i32 s5, s0, 0xffffe000
	s_lshr_b32 s1, s0, 11
	s_lshr_b32 s4, s5, 12
	s_cmpk_lt_i32 s0, 0x2000
	s_cselect_b32 s8, s37, s39
	s_cselect_b32 s9, s36, s38
	s_add_i32 s4, s4, 4
	s_cmpk_lt_i32 s0, 0x2000
	s_cselect_b32 s4, s1, s4
	s_ashr_i32 s1, s0, 31
	s_cmpk_lt_i32 s0, 0x2000
	s_cselect_b32 s7, s1, 0
	s_cselect_b32 s6, s0, s5
	s_lshl_b64 s[10:11], s[0:1], 12
	v_lshl_add_u64 v[0:1], v[24:25], 0, s[10:11]
	global_load_dwordx4 v[2:5], v[26:27], off
	global_load_dwordx2 v[14:15], v[0:1], off
	global_load_dwordx2 v[16:17], v[0:1], off offset:512
	global_load_dwordx2 v[18:19], v[0:1], off offset:1024
	global_load_dwordx2 v[20:21], v[0:1], off offset:1536
	global_load_dwordx2 v[22:23], v[0:1], off offset:2048
	global_load_dwordx2 v[48:49], v[0:1], off offset:2560
	global_load_dwordx2 v[50:51], v[0:1], off offset:3072
	global_load_dwordx2 v[54:55], v[0:1], off offset:3584
	s_mulk_i32 s4, 0x3000
	s_ashr_i32 s5, s4, 31
	s_lshl_b64 s[6:7], s[6:7], 13
	s_add_u32 s6, s9, s6
	s_addc_u32 s7, s8, s7
	s_lshl_b64 s[4:5], s[4:5], 2
	s_add_u32 s12, s2, s4
	s_addc_u32 s13, s3, s5
	s_add_u32 s8, s12, 0x4000
	s_addc_u32 s9, s13, 0
	global_load_dwordx4 v[6:9], v61, s[6:7]
	global_load_dwordx4 v[10:13], v61, s[8:9]
	global_load_dwordx4 v[116:119], v[26:27], off offset:1024
	global_load_dwordx4 v[120:123], v61, s[6:7] offset:1024
	global_load_dwordx4 v[124:127], v62, s[8:9]
	global_load_dwordx4 v[128:131], v[26:27], off offset:2048
	global_load_dwordx4 v[132:135], v61, s[6:7] offset:2048
	global_load_dwordx4 v[136:139], v63, s[8:9]
	global_load_dwordx4 v[140:143], v[26:27], off offset:3072
	global_load_dwordx4 v[144:147], v61, s[6:7] offset:3072
	global_load_dwordx4 v[148:151], v64, s[8:9]
	global_load_dwordx4 v[152:155], v[28:29], off
	global_load_dwordx4 v[156:159], v65, s[6:7]
	global_load_dwordx4 v[160:163], v65, s[8:9]
	global_load_dwordx4 v[164:167], v[30:31], off
	global_load_dwordx4 v[168:171], v66, s[6:7]
	global_load_dwordx4 v[172:175], v66, s[8:9]
	global_load_dwordx4 v[176:179], v[32:33], off
	global_load_dwordx4 v[180:183], v67, s[6:7]
	global_load_dwordx4 v[184:187], v67, s[8:9]
	global_load_dwordx4 v[188:191], v[34:35], off
	global_load_dwordx4 v[192:195], v68, s[6:7]
	global_load_dwordx4 v[196:199], v68, s[8:9]
	s_lshl_b64 s[4:5], s[0:1], 13
	s_add_u32 s4, s28, s4
	s_addc_u32 s5, s29, s5
	s_waitcnt vmcnt(30)
	v_lshlrev_b32_e32 v56, 16, v14
	v_and_b32_e32 v57, 0xffff0000, v14
	s_waitcnt vmcnt(29)
	v_lshlrev_b32_e32 v70, 16, v16
	v_and_b32_e32 v71, 0xffff0000, v16
	v_lshlrev_b32_e32 v14, 16, v15
	s_waitcnt vmcnt(25)
	v_lshlrev_b32_e32 v0, 16, v49
	v_and_b32_e32 v1, 0xffff0000, v49
	s_waitcnt vmcnt(24)
	v_and_b32_e32 v49, 0xffff0000, v50
	s_waitcnt vmcnt(23)
	v_and_b32_e32 v53, 0xffff0000, v54
	v_and_b32_e32 v15, 0xffff0000, v15
	v_lshlrev_b32_e32 v16, 16, v17
	v_and_b32_e32 v17, 0xffff0000, v17
	v_lshlrev_b32_e32 v72, 16, v18
	v_and_b32_e32 v73, 0xffff0000, v18
	v_lshlrev_b32_e32 v74, 16, v19
	v_and_b32_e32 v75, 0xffff0000, v19
	v_lshlrev_b32_e32 v80, 16, v22
	v_and_b32_e32 v81, 0xffff0000, v22
	v_lshlrev_b32_e32 v82, 16, v23
	v_and_b32_e32 v83, 0xffff0000, v23
	v_lshlrev_b32_e32 v84, 16, v48
	v_and_b32_e32 v85, 0xffff0000, v48
	v_lshlrev_b32_e32 v48, 16, v50
	v_lshlrev_b32_e32 v52, 16, v54
	v_pk_mul_f32 v[18:19], v[56:57], v[56:57]
	v_pk_mul_f32 v[22:23], v[70:71], v[70:71]
	v_mov_b32_e32 v106, v49
	v_mov_b32_e32 v107, v53
	v_lshlrev_b32_e32 v76, 16, v20
	v_and_b32_e32 v77, 0xffff0000, v20
	v_lshlrev_b32_e32 v78, 16, v21
	v_and_b32_e32 v79, 0xffff0000, v21
	v_lshlrev_b32_e32 v50, 16, v51
	v_lshlrev_b32_e32 v54, 16, v55
	v_pk_mul_f32 v[20:21], v[14:15], v[14:15]
	v_pk_mul_f32 v[86:87], v[16:17], v[16:17]
	v_pk_mul_f32 v[88:89], v[72:73], v[72:73]
	v_mov_b32_e32 v104, v48
	v_mov_b32_e32 v105, v52
	v_pk_mul_f32 v[106:107], v[106:107], v[106:107]
	v_add_f32_e32 v58, v22, v23
	v_add_f32_e32 v112, v18, v19
	v_and_b32_e32 v51, 0xffff0000, v51
	v_and_b32_e32 v55, 0xffff0000, v55
	v_pk_mul_f32 v[90:91], v[74:75], v[74:75]
	v_pk_mul_f32 v[92:93], v[76:77], v[76:77]
	v_mov_b32_e32 v98, v81
	v_mov_b32_e32 v99, v85
	v_mov_b32_e32 v108, v50
	v_mov_b32_e32 v109, v54
	v_add_f32_e32 v88, v88, v89
	v_pk_fma_f32 v[22:23], v[104:105], v[104:105], v[106:107]
	v_add_f32_e32 v58, v86, v58
	v_add_f32_e32 v20, v20, v112
	v_pk_mul_f32 v[94:95], v[78:79], v[78:79]
	v_mov_b32_e32 v96, v80
	v_mov_b32_e32 v97, v84
	v_mov_b32_e32 v110, v51
	v_mov_b32_e32 v111, v55
	v_pk_mul_f32 v[98:99], v[98:99], v[98:99]
	v_add_f32_e32 v89, v92, v93
	v_add_f32_e32 v86, v90, v88
	v_pk_fma_f32 v[22:23], v[108:109], v[108:109], v[22:23]
	v_add_f32_e32 v58, v87, v58
	v_add_f32_e32 v87, v21, v20
	v_mov_b32_e32 v100, v82
	v_mov_b32_e32 v101, v0
	v_pk_fma_f32 v[18:19], v[96:97], v[96:97], v[98:99]
	v_add_f32_e32 v88, v94, v89
	v_add_f32_e32 v86, v91, v86
	v_pk_fma_f32 v[20:21], v[110:111], v[110:111], v[22:23]
	v_add_f32_e32 v22, v87, v58
	v_mov_b32_e32 v102, v83
	v_mov_b32_e32 v103, v1
	v_pk_fma_f32 v[18:19], v[100:101], v[100:101], v[18:19]
	v_add_f32_e32 v88, v95, v88
	v_add_f32_e32 v22, v22, v86
	v_pk_fma_f32 v[18:19], v[102:103], v[102:103], v[18:19]
	v_add_f32_e32 v22, v22, v88
	v_add_f32_e32 v18, v22, v18
	v_add_f32_e32 v18, v18, v19
	v_add_f32_e32 v18, v18, v20
	v_add_f32_e32 v18, v18, v21
	s_nop 1
	v_add_f32_dpp v18, v18, v18 quad_perm:[1,0,3,2] row_mask:0xf bank_mask:0xf bound_ctrl:1
	s_nop 1
	v_add_f32_dpp v18, v18, v18 quad_perm:[2,3,0,1] row_mask:0xf bank_mask:0xf bound_ctrl:1
	s_nop 1
	v_add_f32_dpp v18, v18, v18 row_half_mirror row_mask:0xf bank_mask:0xf bound_ctrl:1
	s_nop 1
	v_add_f32_dpp v18, v18, v18 row_mirror row_mask:0xf bank_mask:0xf bound_ctrl:1
	ds_bpermute_b32 v19, v59, v18
	s_waitcnt lgkmcnt(0)
; __device__ __forceinline__ void phase_norm2(const Params& p, int wid_s) {
;     ...
;     ss = red64(ss);
;     float rs = rsqrtf(ss * (1.f / 2048.f) + 1e-6f);
;     float ss2 = 0.f;
; #pragma unroll
;     for (int i = 0; i < 8; ++i) {
;       int c = i * 256 + lane * 4;
;       float4 xv = *(const float4*)(xr + c);
;       float4 g = *(const float4*)(p.ln_mix_post + c);
;       float4 gt = *(const float4*)(ad + 4096 + c);
;       mv[i][0] = xv.x + gt.x * (mv[i][0] * rs * g.x);
;       mv[i][1] = xv.y + gt.y * (mv[i][1] * rs * g.y);
;       mv[i][2] = xv.z + gt.z * (mv[i][2] * rs * g.z);
;       mv[i][3] = xv.w + gt.w * (mv[i][3] * rs * g.w);
;       *(float4*)(p.out + (size_t)tok * 2048 + c) = make_float4(mv[i][0], mv[i][1], mv[i][2], mv[i][3]);
;       ss2 += mv[i][0] * mv[i][0] + mv[i][1] * mv[i][1] + mv[i][2] * mv[i][2] + mv[i][3] * mv[i][3];
;     }
;     ...
;       int c = i * 256 + lane * 4;
;       float4 g = *(const float4*)(p.ln_ffn_pre + c);
;       float4 sh = *(const float4*)(ad + 6144 + c);
;       float4 sc = *(const float4*)(ad + 8192 + c);
	v_add_f32_e32 v18, v18, v19
	ds_bpermute_b32 v19, v60, v18
	s_waitcnt lgkmcnt(0)
	v_add_f32_e32 v18, v18, v19
	v_fmamk_f32 v18, v18, 0x3a000000, v69
	v_mul_f32_e32 v19, 0x4b800000, v18
	v_cmp_gt_f32_e32 vcc, s15, v18
	s_nop 1
	v_cndmask_b32_e32 v18, v18, v19, vcc
	v_rsq_f32_e32 v18, v18
	s_nop 0
	v_mul_f32_e32 v19, 0x45800000, v18
	v_cndmask_b32_e32 v58, v18, v19, vcc
	v_pk_mul_f32 v[18:19], v[58:59], v[56:57] op_sel_hi:[0,1]
	v_pk_mul_f32 v[14:15], v[58:59], v[14:15] op_sel_hi:[0,1]
	v_pk_mul_f32 v[2:3], v[2:3], v[18:19]
	v_pk_mul_f32 v[4:5], v[4:5], v[14:15]
	s_waitcnt vmcnt(0)
	v_pk_fma_f32 v[20:21], v[10:11], v[2:3], v[6:7]
	v_pk_fma_f32 v[22:23], v[12:13], v[4:5], v[8:9]
	global_store_dwordx4 v61, v[20:23], s[4:5]
	v_pk_mul_f32 v[14:15], v[58:59], v[70:71] op_sel_hi:[0,1]
	v_pk_mul_f32 v[16:17], v[58:59], v[16:17] op_sel_hi:[0,1]
	v_pk_mul_f32 v[56:57], v[58:59], v[74:75] op_sel_hi:[0,1]
	v_pk_mul_f32 v[0:1], v[58:59], v[0:1] op_sel_hi:[0,1]
	v_pk_mul_f32 v[48:49], v[58:59], v[48:49] op_sel_hi:[0,1]
	v_pk_mul_f32 v[50:51], v[58:59], v[50:51] op_sel_hi:[0,1]
	v_pk_mul_f32 v[86:87], v[22:23], v[22:23]
	v_pk_mul_f32 v[2:3], v[14:15], v[116:117]
	v_pk_mul_f32 v[4:5], v[16:17], v[118:119]
	v_pk_fma_f32 v[16:17], v[2:3], v[124:125], v[120:121]
	v_pk_fma_f32 v[18:19], v[4:5], v[126:127], v[122:123]
	global_store_dwordx4 v61, v[16:19], s[4:5] offset:1024
	v_pk_mul_f32 v[10:11], v[58:59], v[72:73] op_sel_hi:[0,1]
	v_pk_mul_f32 v[2:3], v[10:11], v[128:129]
	v_pk_mul_f32 v[4:5], v[56:57], v[130:131]
	v_pk_fma_f32 v[12:13], v[2:3], v[136:137], v[132:133]
	v_pk_fma_f32 v[14:15], v[4:5], v[138:139], v[134:135]
	global_store_dwordx4 v61, v[12:15], s[4:5] offset:2048
	v_pk_mul_f32 v[6:7], v[58:59], v[76:77] op_sel_hi:[0,1]
	v_pk_mul_f32 v[56:57], v[58:59], v[78:79] op_sel_hi:[0,1]
	v_pk_mul_f32 v[2:3], v[6:7], v[140:141]
	v_pk_mul_f32 v[4:5], v[56:57], v[142:143]
	v_pk_fma_f32 v[8:9], v[2:3], v[148:149], v[144:145]
	v_pk_fma_f32 v[10:11], v[4:5], v[150:151], v[146:147]
	global_store_dwordx4 v61, v[8:11], s[4:5] offset:3072
	v_pk_mul_f32 v[6:7], v[58:59], v[80:81] op_sel_hi:[0,1]
	v_pk_mul_f32 v[56:57], v[58:59], v[82:83] op_sel_hi:[0,1]
	v_pk_mul_f32 v[82:83], v[58:59], v[52:53] op_sel_hi:[0,1]
	v_pk_mul_f32 v[52:53], v[20:21], v[20:21]
	v_pk_mul_f32 v[2:3], v[6:7], v[152:153]
	v_pk_mul_f32 v[6:7], v[56:57], v[154:155]
	v_pk_fma_f32 v[4:5], v[2:3], v[160:161], v[156:157]
	v_pk_fma_f32 v[6:7], v[6:7], v[162:163], v[158:159]
	global_store_dwordx4 v65, v[4:7], s[4:5]
	v_pk_mul_f32 v[2:3], v[58:59], v[84:85] op_sel_hi:[0,1]
	v_add_f32_e32 v52, v52, v53
	v_pk_mul_f32 v[84:85], v[58:59], v[54:55] op_sel_hi:[0,1]
	v_add_f32_e32 v58, v86, v52
	v_add_f32_e32 v58, v87, v58
	v_mov_b32_e32 v86, v6
	v_mov_b32_e32 v88, v7
	v_pk_mul_f32 v[2:3], v[2:3], v[164:165]
	v_pk_mul_f32 v[56:57], v[0:1], v[166:167]
	v_pk_fma_f32 v[0:1], v[2:3], v[172:173], v[168:169]
	v_pk_fma_f32 v[2:3], v[56:57], v[174:175], v[170:171]
	global_store_dwordx4 v66, v[0:3], s[4:5]
	v_mov_b32_e32 v87, v2
	v_lshl_add_u64 v[56:57], v[46:47], 0, s[10:11]
	s_add_u32 s10, s12, 0x6000
	v_mov_b32_e32 v89, v3
	s_addc_u32 s11, s13, 0
	s_add_u32 s12, s12, 0x8000
	s_addc_u32 s13, s13, 0
	s_add_i32 s16, s16, s33
	s_add_i32 s0, s0, s14
	s_cmpk_lt_i32 s16, 0x1400
	v_pk_mul_f32 v[48:49], v[48:49], v[176:177]
	v_pk_mul_f32 v[50:51], v[50:51], v[178:179]
	v_pk_fma_f32 v[48:49], v[48:49], v[184:185], v[180:181]
	v_pk_fma_f32 v[50:51], v[50:51], v[186:187], v[182:183]
	global_store_dwordx4 v67, v[48:51], s[4:5]
	v_pk_mul_f32 v[78:79], v[16:17], v[16:17]
	v_pk_mul_f32 v[80:81], v[18:19], v[18:19]
	v_add_f32_e32 v78, v78, v79
	v_add_f32_e32 v78, v80, v78
	v_add_f32_e32 v78, v81, v78
	v_add_f32_e32 v58, v58, v78
	v_pk_mul_f32 v[78:79], v[12:13], v[12:13]
	v_pk_mul_f32 v[80:81], v[14:15], v[14:15]
	v_add_f32_e32 v78, v78, v79
	v_add_f32_e32 v78, v80, v78
	v_add_f32_e32 v78, v81, v78
	v_add_f32_e32 v58, v58, v78
	v_pk_mul_f32 v[78:79], v[8:9], v[8:9]
	v_pk_mul_f32 v[80:81], v[10:11], v[10:11]
	v_add_f32_e32 v78, v78, v79
	v_add_f32_e32 v78, v80, v78
	v_add_f32_e32 v78, v81, v78
	v_mov_b32_e32 v80, v5
	v_mov_b32_e32 v81, v1
	v_add_f32_e32 v58, v58, v78
	v_mov_b32_e32 v78, v4
	v_mov_b32_e32 v79, v0
	v_pk_mul_f32 v[80:81], v[80:81], v[80:81]
	v_mov_b32_e32 v90, v50
	v_pk_fma_f32 v[78:79], v[78:79], v[78:79], v[80:81]
	v_pk_mul_f32 v[52:53], v[82:83], v[188:189]
	v_pk_fma_f32 v[78:79], v[86:87], v[86:87], v[78:79]
	v_pk_mul_f32 v[54:55], v[84:85], v[190:191]
	v_pk_fma_f32 v[78:79], v[88:89], v[88:89], v[78:79]
	v_pk_fma_f32 v[52:53], v[52:53], v[196:197], v[192:193]
	v_pk_fma_f32 v[54:55], v[54:55], v[198:199], v[194:195]
	v_add_f32_e32 v58, v58, v78
	global_store_dwordx4 v68, v[52:55], s[4:5]
	v_add_f32_e32 v58, v58, v79
	global_load_dwordx4 v[70:73], v[36:37], off
	global_load_dwordx4 v[74:77], v61, s[12:13]
	global_load_dwordx4 v[78:81], v61, s[10:11]
	global_load_dwordx4 v[116:119], v[36:37], off offset:1024
	global_load_dwordx4 v[120:123], v62, s[12:13]
	global_load_dwordx4 v[124:127], v62, s[10:11]
	global_load_dwordx4 v[128:131], v[36:37], off offset:2048
	global_load_dwordx4 v[132:135], v63, s[12:13]
	global_load_dwordx4 v[136:139], v63, s[10:11]
	global_load_dwordx4 v[140:143], v[36:37], off offset:3072
	global_load_dwordx4 v[144:147], v64, s[12:13]
	global_load_dwordx4 v[148:151], v64, s[10:11]
	global_load_dwordx4 v[152:155], v[38:39], off
	global_load_dwordx4 v[156:159], v65, s[12:13]
	global_load_dwordx4 v[160:163], v65, s[10:11]
	global_load_dwordx4 v[164:167], v[40:41], off
	global_load_dwordx4 v[168:171], v66, s[12:13]
	global_load_dwordx4 v[172:175], v66, s[10:11]
	global_load_dwordx4 v[176:179], v[42:43], off
	global_load_dwordx4 v[180:183], v67, s[12:13]
	global_load_dwordx4 v[184:187], v67, s[10:11]
	global_load_dwordx4 v[188:191], v[44:45], off
	global_load_dwordx4 v[192:195], v68, s[12:13]
	global_load_dwordx4 v[196:199], v68, s[10:11]
	v_mov_b32_e32 v88, v49
	v_mov_b32_e32 v89, v53
	v_mov_b32_e32 v86, v48
	v_mov_b32_e32 v87, v52
	v_pk_mul_f32 v[84:85], v[88:89], v[88:89]
	v_mov_b32_e32 v91, v54
	v_pk_fma_f32 v[84:85], v[86:87], v[86:87], v[84:85]
	v_mov_b32_e32 v82, v51
	v_mov_b32_e32 v83, v55
	v_pk_fma_f32 v[84:85], v[90:91], v[90:91], v[84:85]
	s_nop 0
	v_pk_fma_f32 v[82:83], v[82:83], v[82:83], v[84:85]
	s_nop 0
	v_add_f32_e32 v58, v58, v82
	v_add_f32_e32 v58, v58, v83
	s_nop 1
	v_add_f32_dpp v58, v58, v58 quad_perm:[1,0,3,2] row_mask:0xf bank_mask:0xf bound_ctrl:1
	s_nop 1
	v_add_f32_dpp v58, v58, v58 quad_perm:[2,3,0,1] row_mask:0xf bank_mask:0xf bound_ctrl:1
	s_nop 1
	v_add_f32_dpp v58, v58, v58 row_half_mirror row_mask:0xf bank_mask:0xf bound_ctrl:1
	s_nop 1
	v_add_f32_dpp v58, v58, v58 row_mirror row_mask:0xf bank_mask:0xf bound_ctrl:1
	ds_bpermute_b32 v82, v59, v58
	s_waitcnt lgkmcnt(0)
; __device__ __forceinline__ void phase_norm2(const Params& p, int wid_s) {
;     ...
;     ss2 = red64(ss2);
;     float rs2 = rsqrtf(ss2 * (1.f / 2048.f) + 1e-6f);
; #pragma unroll
;     for (int i = 0; i < 8; ++i) {
;       int c = i * 256 + lane * 4;
;       float4 g = *(const float4*)(p.ln_ffn_pre + c);
;       float4 sh = *(const float4*)(ad + 6144 + c);
;       float4 sc = *(const float4*)(ad + 8192 + c);
;       uint2 o;
;       o.x = pack2(mv[i][0] * rs2 * g.x * (1.f + sc.x) + sh.x, mv[i][1] * rs2 * g.y * (1.f + sc.y) + sh.y);
;       o.y = pack2(mv[i][2] * rs2 * g.z * (1.f + sc.z) + sh.z, mv[i][3] * rs2 * g.w * (1.f + sc.w) + sh.w);
;       *(uint2*)(H + (size_t)tok * 2048 + c) = o;
;     }
	v_add_f32_e32 v58, v58, v82
	ds_bpermute_b32 v82, v60, v58
	s_waitcnt lgkmcnt(0)
	v_add_f32_e32 v58, v58, v82
	v_fmamk_f32 v58, v58, 0x3a000000, v69
	v_mul_f32_e32 v82, 0x4b800000, v58
	v_cmp_gt_f32_e32 vcc, s15, v58
	s_nop 1
	v_cndmask_b32_e32 v58, v58, v82, vcc
	v_rsq_f32_e32 v58, v58
	s_nop 0
	v_mul_f32_e32 v82, 0x45800000, v58
	v_cndmask_b32_e32 v58, v58, v82, vcc
	v_pk_mul_f32 v[20:21], v[20:21], v[58:59] op_sel_hi:[1,0]
	v_pk_mul_f32 v[22:23], v[22:23], v[58:59] op_sel_hi:[1,0]
	v_pk_mul_f32 v[16:17], v[16:17], v[58:59] op_sel_hi:[1,0]
	v_pk_mul_f32 v[18:19], v[18:19], v[58:59] op_sel_hi:[1,0]
	v_pk_mul_f32 v[12:13], v[12:13], v[58:59] op_sel_hi:[1,0]
	v_pk_mul_f32 v[14:15], v[14:15], v[58:59] op_sel_hi:[1,0]
	v_pk_mul_f32 v[8:9], v[8:9], v[58:59] op_sel_hi:[1,0]
	v_pk_mul_f32 v[10:11], v[10:11], v[58:59] op_sel_hi:[1,0]
	v_pk_mul_f32 v[4:5], v[4:5], v[58:59] op_sel_hi:[1,0]
	v_pk_mul_f32 v[6:7], v[6:7], v[58:59] op_sel_hi:[1,0]
	v_pk_mul_f32 v[0:1], v[0:1], v[58:59] op_sel_hi:[1,0]
	v_pk_mul_f32 v[2:3], v[2:3], v[58:59] op_sel_hi:[1,0]
	s_waitcnt vmcnt(23)
	v_pk_mul_f32 v[20:21], v[70:71], v[20:21]
	s_waitcnt vmcnt(22)
	v_pk_add_f32 v[70:71], v[74:75], 1.0 op_sel_hi:[1,0]
	v_pk_mul_f32 v[22:23], v[72:73], v[22:23]
	v_pk_add_f32 v[72:73], v[76:77], 1.0 op_sel_hi:[1,0]
	s_waitcnt vmcnt(0)
	v_pk_fma_f32 v[20:21], v[70:71], v[20:21], v[78:79]
	v_pk_fma_f32 v[22:23], v[22:23], v[72:73], v[80:81]
	v_cvt_pk_bf16_f32 v20, v20, v21
	v_cvt_pk_bf16_f32 v21, v22, v23
	global_store_dwordx2 v[56:57], v[20:21], off
	s_nop 0
	v_pk_mul_f32 v[16:17], v[16:17], v[116:117]
	v_pk_add_f32 v[20:21], v[120:121], 1.0 op_sel_hi:[1,0]
	v_pk_mul_f32 v[18:19], v[18:19], v[118:119]
	v_pk_add_f32 v[22:23], v[122:123], 1.0 op_sel_hi:[1,0]
	v_pk_fma_f32 v[16:17], v[16:17], v[20:21], v[124:125]
	v_pk_fma_f32 v[18:19], v[18:19], v[22:23], v[126:127]
	v_cvt_pk_bf16_f32 v16, v16, v17
	v_cvt_pk_bf16_f32 v17, v18, v19
	global_store_dwordx2 v[56:57], v[16:17], off offset:512
	s_nop 0
	v_pk_mul_f32 v[12:13], v[12:13], v[128:129]
	v_pk_add_f32 v[16:17], v[132:133], 1.0 op_sel_hi:[1,0]
	v_pk_mul_f32 v[14:15], v[14:15], v[130:131]
	v_pk_add_f32 v[18:19], v[134:135], 1.0 op_sel_hi:[1,0]
	v_pk_fma_f32 v[12:13], v[12:13], v[16:17], v[136:137]
	v_pk_fma_f32 v[14:15], v[14:15], v[18:19], v[138:139]
	v_cvt_pk_bf16_f32 v12, v12, v13
	v_cvt_pk_bf16_f32 v13, v14, v15
	global_store_dwordx2 v[56:57], v[12:13], off offset:1024
	s_nop 0
	v_pk_mul_f32 v[8:9], v[8:9], v[140:141]
	v_pk_add_f32 v[12:13], v[144:145], 1.0 op_sel_hi:[1,0]
	v_pk_mul_f32 v[10:11], v[10:11], v[142:143]
	v_pk_add_f32 v[14:15], v[146:147], 1.0 op_sel_hi:[1,0]
	v_pk_fma_f32 v[8:9], v[8:9], v[12:13], v[148:149]
	v_pk_fma_f32 v[10:11], v[10:11], v[14:15], v[150:151]
	v_cvt_pk_bf16_f32 v8, v8, v9
	v_cvt_pk_bf16_f32 v9, v10, v11
	global_store_dwordx2 v[56:57], v[8:9], off offset:1536
	s_nop 0
	v_pk_mul_f32 v[4:5], v[4:5], v[152:153]
	v_pk_add_f32 v[8:9], v[156:157], 1.0 op_sel_hi:[1,0]
	v_pk_mul_f32 v[6:7], v[6:7], v[154:155]
	v_pk_add_f32 v[10:11], v[158:159], 1.0 op_sel_hi:[1,0]
	v_pk_fma_f32 v[4:5], v[4:5], v[8:9], v[160:161]
	v_pk_fma_f32 v[6:7], v[6:7], v[10:11], v[162:163]
	v_cvt_pk_bf16_f32 v4, v4, v5
	v_cvt_pk_bf16_f32 v5, v6, v7
	global_store_dwordx2 v[56:57], v[4:5], off offset:2048
	s_nop 0
	v_pk_mul_f32 v[0:1], v[0:1], v[164:165]
	v_pk_add_f32 v[4:5], v[168:169], 1.0 op_sel_hi:[1,0]
	v_pk_mul_f32 v[2:3], v[2:3], v[166:167]
	v_pk_add_f32 v[6:7], v[170:171], 1.0 op_sel_hi:[1,0]
	v_pk_fma_f32 v[0:1], v[0:1], v[4:5], v[172:173]
	v_pk_fma_f32 v[2:3], v[2:3], v[6:7], v[174:175]
	v_cvt_pk_bf16_f32 v0, v0, v1
	v_cvt_pk_bf16_f32 v1, v2, v3
	global_store_dwordx2 v[56:57], v[0:1], off offset:2560
	s_nop 0
	v_pk_mul_f32 v[12:13], v[48:49], v[58:59] op_sel_hi:[1,0]
	v_pk_mul_f32 v[14:15], v[50:51], v[58:59] op_sel_hi:[1,0]
	v_pk_mul_f32 v[0:1], v[12:13], v[176:177]
	v_pk_add_f32 v[4:5], v[180:181], 1.0 op_sel_hi:[1,0]
	v_pk_mul_f32 v[2:3], v[14:15], v[178:179]
	v_pk_add_f32 v[6:7], v[182:183], 1.0 op_sel_hi:[1,0]
	v_pk_fma_f32 v[0:1], v[0:1], v[4:5], v[184:185]
	v_pk_fma_f32 v[2:3], v[2:3], v[6:7], v[186:187]
	v_cvt_pk_bf16_f32 v0, v0, v1
	v_cvt_pk_bf16_f32 v1, v2, v3
	global_store_dwordx2 v[56:57], v[0:1], off offset:3072
	s_nop 0
	v_pk_mul_f32 v[12:13], v[52:53], v[58:59] op_sel_hi:[1,0]
	v_pk_mul_f32 v[14:15], v[54:55], v[58:59] op_sel_hi:[1,0]
	v_pk_mul_f32 v[0:1], v[12:13], v[188:189]
	v_pk_add_f32 v[4:5], v[192:193], 1.0 op_sel_hi:[1,0]
	v_pk_mul_f32 v[2:3], v[14:15], v[190:191]
	v_pk_add_f32 v[6:7], v[194:195], 1.0 op_sel_hi:[1,0]
	v_pk_fma_f32 v[0:1], v[0:1], v[4:5], v[196:197]
	v_pk_fma_f32 v[2:3], v[2:3], v[6:7], v[198:199]
	v_cvt_pk_bf16_f32 v0, v0, v1
	v_cvt_pk_bf16_f32 v1, v2, v3
	global_store_dwordx2 v[56:57], v[0:1], off offset:3584
	s_cbranch_scc1 .LBB0_1020

; __device__ __forceinline__ float bflo(unsigned u) { return __uint_as_float(u << 16); }
; __device__ __forceinline__ float bfhi(unsigned u) { return __uint_as_float(u & 0xffff0000u); }
; __device__ __forceinline__ float tanhf_(float x) { return 1.f - 2.f * __builtin_amdgcn_rcpf(1.f + __expf(2.f * x)); }
; __device__ __forceinline__ void phase_gemm5(const Params& p, int wid_s, char* shm) {
;     ...
;           for (int j = 0; j < 4; ++j) {
;             int r = ai * 128 + rbase + m * 16 + j;
;             bool doit = (r >= 1 || seq_first) && (r <= 254 || seq_last);
;             if (doit) {
;               unsigned gp = (r >= 1) ? *(const unsigned*)(gs_ + (r - 1) * 130 + cl) : 0u;
;               unsigned gn = (r <= 254) ? *(const unsigned*)(gs_ + (r + 1) * 130 + cl) : 0u;
;               float u0 = cw0.x * bflo(gp) + cw1.x * acc[ai][0][m][0][j] + cw2.x * bflo(gn) + cbv.x;
;               float u1 = cw0.y * bfhi(gp) + cw1.y * acc[ai][0][m][1][j] + cw2.y * bfhi(gn) + cbv.y;
;               float i0 = 0.7978845608028654f * (u0 + 0.044715f * u0 * u0 * u0);
;               float i1 = 0.7978845608028654f * (u1 + 0.044715f * u1 * u1 * u1);
;               float g0 = 0.5f * u0 * (1.f + tanhf_(i0));
;               float g1 = 0.5f * u1 * (1.f + tanhf_(i1));
;               *(unsigned*)(ACT + (size_t)(brow + r) * 5504 + f) = pack2(g0 * acc[ai][1][m][0][j], g1 * acc[ai][1][m][1][j]);
.LBB0_1045:
	s_or_b64 exec, exec, s[0:1]
	s_waitcnt lgkmcnt(0)
	v_lshlrev_b32_e32 v4, 16, v1
	v_and_b32_e32 v5, 0xffff0000, v1
	v_lshlrev_b32_e32 v8, 16, v0
	v_and_b32_e32 v9, 0xffff0000, v0
	s_waitcnt vmcnt(3)
	v_pk_mul_f32 v[0:1], v[108:109], v[4:5]
	v_mov_b32_e32 v6, v3
	s_waitcnt vmcnt(2)
	v_pk_fma_f32 v[0:1], v[10:11], v[110:111], v[0:1]
	s_waitcnt vmcnt(1)
	v_pk_fma_f32 v[0:1], v[104:105], v[8:9], v[0:1]
	s_waitcnt vmcnt(0)
	v_pk_add_f32 v[0:1], v[106:107], v[0:1]
	s_nop 0
	v_mul_f32_e32 v2, 0x3d372713, v0
	v_mul_f32_e32 v2, v0, v2
	v_mul_f32_e32 v4, 0x3d372713, v1
	v_fma_f32 v2, v0, v2, v0
	v_mul_f32_e32 v4, v1, v4
	v_mul_f32_e32 v2, 0x3f4c422a, v2
	v_fma_f32 v4, v1, v4, v1
	v_mul_f32_e32 v4, 0x3f4c422a, v4
	v_add_f32_e32 v2, v2, v2
	v_mul_f32_e32 v2, 0x3fb8aa3b, v2
	v_add_f32_e32 v4, v4, v4
	v_exp_f32_e32 v2, v2
	v_mul_f32_e32 v4, 0x3fb8aa3b, v4
	v_exp_f32_e32 v5, v4
	v_pk_mul_f32 v[0:1], v[0:1], 0.5 op_sel_hi:[1,0]
	v_add_f32_e32 v2, 1.0, v2
	v_rcp_f32_e32 v4, v2
	v_add_f32_e32 v2, 1.0, v5
	v_rcp_f32_e32 v5, v2
	s_nop 0
	v_pk_fma_f32 v[4:5], v[4:5], -2.0, 1.0 op_sel_hi:[1,0,0]
	s_nop 0
	v_pk_add_f32 v[4:5], v[4:5], 1.0 op_sel_hi:[1,0]
	s_nop 0
	v_pk_mul_f32 v[0:1], v[0:1], v[4:5]
	s_nop 0
	v_pk_mul_f32 v[0:1], v[6:7], v[0:1]
	s_nop 0
	v_cvt_pk_bf16_f32 v2, v0, v1
	v_add_u32_e32 v0, s54, v96
	v_mad_i64_i32 v[0:1], s[0:1], v0, s87, v[98:99]
	global_store_dword v[0:1], v2, off

; __device__ __forceinline__ float bflo(unsigned u) { return __uint_as_float(u << 16); }
; __device__ __forceinline__ float bfhi(unsigned u) { return __uint_as_float(u & 0xffff0000u); }
; __device__ __forceinline__ float tanhf_(float x) { return 1.f - 2.f * __builtin_amdgcn_rcpf(1.f + __expf(2.f * x)); }
; __device__ __forceinline__ void phase_gemm5(const Params& p, int wid_s, char* shm) {
;     ...
;           for (int j = 0; j < 4; ++j) {
;             int r = ai * 128 + rbase + m * 16 + j;
;             bool doit = (r >= 1 || seq_first) && (r <= 254 || seq_last);
;             if (doit) {
;               unsigned gp = (r >= 1) ? *(const unsigned*)(gs_ + (r - 1) * 130 + cl) : 0u;
;               unsigned gn = (r <= 254) ? *(const unsigned*)(gs_ + (r + 1) * 130 + cl) : 0u;
;               float u0 = cw0.x * bflo(gp) + cw1.x * acc[ai][0][m][0][j] + cw2.x * bflo(gn) + cbv.x;
;               float u1 = cw0.y * bfhi(gp) + cw1.y * acc[ai][0][m][1][j] + cw2.y * bfhi(gn) + cbv.y;
;               float i0 = 0.7978845608028654f * (u0 + 0.044715f * u0 * u0 * u0);
;               float i1 = 0.7978845608028654f * (u1 + 0.044715f * u1 * u1 * u1);
;               float g0 = 0.5f * u0 * (1.f + tanhf_(i0));
;               float g1 = 0.5f * u1 * (1.f + tanhf_(i1));
;               *(unsigned*)(ACT + (size_t)(brow + r) * 5504 + f) = pack2(g0 * acc[ai][1][m][0][j], g1 * acc[ai][1][m][1][j]);
;             }
.LBB0_1086:
	s_or_b64 exec, exec, s[60:61]
	v_cmp_lt_i32_e32 vcc, -1, v130
	v_cmp_gt_i32_e64 s[0:1], s91, v144
	s_or_b64 s[60:61], vcc, s[56:57]
	s_or_b64 s[62:63], s[0:1], s[58:59]
	s_and_b64 s[64:65], s[60:61], s[62:63]
	s_and_saveexec_b64 s[62:63], s[64:65]
	s_cbranch_execz .LBB0_1092
	v_mov_b32_e32 v84, 0
	v_mov_b32_e32 v88, 0
	s_and_saveexec_b64 s[64:65], vcc
	v_add3_u32 v88, v184, v156, s92
	ds_read_b32 v88, v88
	s_or_b64 exec, exec, s[64:65]
	s_and_saveexec_b64 s[64:65], s[0:1]
	v_lshl_add_u32 v84, v155, 1, v184
	ds_read_b32 v84, v84 offset:260
	s_or_b64 exec, exec, s[64:65]
	s_waitcnt lgkmcnt(0)
	v_lshlrev_b32_e32 v146, 16, v88
	v_and_b32_e32 v147, 0xffff0000, v88
	s_waitcnt vmcnt(3)
	v_pk_mul_f32 v[146:147], v[108:109], v[146:147]
	v_lshlrev_b32_e32 v148, 16, v84
	v_and_b32_e32 v149, 0xffff0000, v84
	s_waitcnt vmcnt(2)
	v_pk_fma_f32 v[92:93], v[92:93], v[110:111], v[146:147]
	s_waitcnt vmcnt(1)
	v_pk_fma_f32 v[92:93], v[104:105], v[148:149], v[92:93]
	s_waitcnt vmcnt(0)
	v_pk_add_f32 v[92:93], v[106:107], v[92:93]
	s_nop 0
	v_mul_f32_e32 v84, 0x3d372713, v92
	v_mul_f32_e32 v84, v92, v84
	v_mul_f32_e32 v88, 0x3d372713, v93
	v_fma_f32 v84, v92, v84, v92
	v_mul_f32_e32 v88, v93, v88
	v_mul_f32_e32 v84, 0x3f4c422a, v84
	v_fma_f32 v88, v93, v88, v93
	v_mul_f32_e32 v88, 0x3f4c422a, v88
	v_add_f32_e32 v84, v84, v84
	v_mul_f32_e32 v84, 0x3fb8aa3b, v84
	v_add_f32_e32 v88, v88, v88
	v_exp_f32_e32 v84, v84
	v_mul_f32_e32 v88, 0x3fb8aa3b, v88
	v_exp_f32_e32 v88, v88
	v_pk_mul_f32 v[92:93], v[92:93], 0.5 op_sel_hi:[1,0]
	v_add_f32_e32 v84, 1.0, v84
	v_rcp_f32_e32 v146, v84
	v_add_f32_e32 v84, 1.0, v88
	v_rcp_f32_e32 v147, v84
	v_mov_b32_e32 v88, v85
	v_pk_fma_f32 v[146:147], v[146:147], -2.0, 1.0 op_sel_hi:[1,0,0]
	s_nop 0
	v_pk_add_f32 v[146:147], v[146:147], 1.0 op_sel_hi:[1,0]
	s_nop 0
	v_pk_mul_f32 v[92:93], v[92:93], v[146:147]
	s_nop 0
	v_pk_mul_f32 v[84:85], v[88:89], v[92:93]
	s_nop 0
	v_cvt_pk_bf16_f32 v88, v84, v85
	v_add_u32_e32 v84, s54, v144
	v_mad_i64_i32 v[84:85], s[0:1], v84, s87, v[98:99]
	global_store_dword v[84:85], v88, off
.LBB0_1092:
	s_or_b64 exec, exec, s[62:63]
	v_or_b32_e32 v84, 2, v130
	v_cmp_gt_i32_e64 s[0:1], s91, v84
	s_or_b64 s[62:63], s[0:1], s[58:59]
	s_and_b64 s[64:65], s[60:61], s[62:63]
	s_and_saveexec_b64 s[62:63], s[64:65]
	s_cbranch_execz .LBB0_1098
	v_mov_b32_e32 v85, 0
	v_mov_b32_e32 v88, 0
	s_and_saveexec_b64 s[64:65], vcc
	v_add3_u32 v88, v183, v156, s92
	ds_read_b32 v88, v88
	s_or_b64 exec, exec, s[64:65]
	s_and_saveexec_b64 s[64:65], s[0:1]
	v_lshl_add_u32 v85, v155, 1, v183
	ds_read_b32 v85, v85 offset:260
	s_or_b64 exec, exec, s[64:65]
	s_waitcnt lgkmcnt(0)
	v_lshlrev_b32_e32 v92, 16, v88
	v_and_b32_e32 v93, 0xffff0000, v88
	s_waitcnt vmcnt(3)
	v_pk_mul_f32 v[88:89], v[108:109], v[92:93]
	v_lshlrev_b32_e32 v146, 16, v85
	v_and_b32_e32 v147, 0xffff0000, v85
	s_waitcnt vmcnt(2)
	v_pk_fma_f32 v[88:89], v[142:143], v[110:111], v[88:89]
	v_add_u32_e32 v84, s54, v84
	s_waitcnt vmcnt(1)
	v_pk_fma_f32 v[88:89], v[104:105], v[146:147], v[88:89]
	s_waitcnt vmcnt(0)
	v_pk_add_f32 v[88:89], v[106:107], v[88:89]
	s_nop 0
	v_mul_f32_e32 v85, 0x3d372713, v88
	v_mul_f32_e32 v85, v88, v85
	v_mul_f32_e32 v92, 0x3d372713, v89
	v_fma_f32 v85, v88, v85, v88
	v_mul_f32_e32 v92, v89, v92
	v_mul_f32_e32 v85, 0x3f4c422a, v85
	v_fma_f32 v92, v89, v92, v89
	v_mul_f32_e32 v92, 0x3f4c422a, v92
	v_add_f32_e32 v85, v85, v85
	v_mul_f32_e32 v85, 0x3fb8aa3b, v85
	v_add_f32_e32 v92, v92, v92
	v_exp_f32_e32 v85, v85
	v_mul_f32_e32 v92, 0x3fb8aa3b, v92
	v_exp_f32_e32 v93, v92
	v_pk_mul_f32 v[88:89], v[88:89], 0.5 op_sel_hi:[1,0]
	v_add_f32_e32 v85, 1.0, v85
	v_rcp_f32_e32 v92, v85
	v_add_f32_e32 v85, 1.0, v93
	v_rcp_f32_e32 v93, v85
	v_mad_i64_i32 v[84:85], s[0:1], v84, s87, v[98:99]
	v_pk_fma_f32 v[92:93], v[92:93], -2.0, 1.0 op_sel_hi:[1,0,0]
	s_nop 0
	v_pk_add_f32 v[92:93], v[92:93], 1.0 op_sel_hi:[1,0]
	s_nop 0
	v_pk_mul_f32 v[88:89], v[88:89], v[92:93]
	v_mov_b32_e32 v92, v86
	v_mov_b32_e32 v93, v90
	v_pk_mul_f32 v[88:89], v[92:93], v[88:89]
	s_nop 0
	v_cvt_pk_bf16_f32 v86, v88, v89
	global_store_dword v[84:85], v86, off
.LBB0_1098:
	s_or_b64 exec, exec, s[62:63]
	v_or_b32_e32 v84, 3, v130
	v_cmp_gt_i32_e64 s[0:1], s91, v84
	s_or_b64 s[62:63], s[0:1], s[58:59]
	s_and_b64 s[62:63], s[60:61], s[62:63]
	s_and_saveexec_b64 s[60:61], s[62:63]
	s_cbranch_execz .LBB0_1104
	v_mov_b32_e32 v85, 0
	v_mov_b32_e32 v86, 0
	s_and_saveexec_b64 s[62:63], vcc
	v_add3_u32 v86, v182, v156, s92
	ds_read_b32 v86, v86
	s_or_b64 exec, exec, s[62:63]
	s_and_saveexec_b64 s[62:63], s[0:1]
	v_lshl_add_u32 v85, v155, 1, v182
	ds_read_b32 v85, v85 offset:260
	s_or_b64 exec, exec, s[62:63]
	s_waitcnt lgkmcnt(0)
	v_lshlrev_b32_e32 v88, 16, v86
	v_and_b32_e32 v89, 0xffff0000, v86
	s_waitcnt vmcnt(3)
	v_pk_mul_f32 v[88:89], v[108:109], v[88:89]
	v_lshlrev_b32_e32 v92, 16, v85
	v_and_b32_e32 v93, 0xffff0000, v85
	s_waitcnt vmcnt(2)
	v_pk_fma_f32 v[88:89], v[94:95], v[110:111], v[88:89]
	v_mov_b32_e32 v90, v87
	s_waitcnt vmcnt(1)
	v_pk_fma_f32 v[88:89], v[104:105], v[92:93], v[88:89]
	v_add_u32_e32 v84, s54, v84
	s_waitcnt vmcnt(0)
	v_pk_add_f32 v[88:89], v[106:107], v[88:89]
	s_nop 0
	v_mul_f32_e32 v85, 0x3d372713, v88
	v_mul_f32_e32 v85, v88, v85
	v_mul_f32_e32 v86, 0x3d372713, v89
	v_fma_f32 v85, v88, v85, v88
	v_mul_f32_e32 v86, v89, v86
	v_mul_f32_e32 v85, 0x3f4c422a, v85
	v_fma_f32 v86, v89, v86, v89
	v_mul_f32_e32 v86, 0x3f4c422a, v86
	v_add_f32_e32 v85, v85, v85
	v_mul_f32_e32 v85, 0x3fb8aa3b, v85
	v_add_f32_e32 v86, v86, v86
	v_exp_f32_e32 v85, v85
	v_mul_f32_e32 v86, 0x3fb8aa3b, v86
	v_exp_f32_e32 v86, v86
	v_pk_mul_f32 v[88:89], v[88:89], 0.5 op_sel_hi:[1,0]
	v_add_f32_e32 v85, 1.0, v85
	v_rcp_f32_e32 v92, v85
	v_add_f32_e32 v85, 1.0, v86
	v_rcp_f32_e32 v93, v85
	v_mad_i64_i32 v[84:85], s[0:1], v84, s87, v[98:99]
	v_pk_fma_f32 v[92:93], v[92:93], -2.0, 1.0 op_sel_hi:[1,0,0]
	s_nop 0
	v_pk_add_f32 v[92:93], v[92:93], 1.0 op_sel_hi:[1,0]
	s_nop 0
	v_pk_mul_f32 v[88:89], v[88:89], v[92:93]
	s_nop 0
	v_pk_mul_f32 v[86:87], v[90:91], v[88:89]
	s_nop 0
	v_cvt_pk_bf16_f32 v86, v86, v87
	global_store_dword v[84:85], v86, off
; __device__ __forceinline__ float bflo(unsigned u) { return __uint_as_float(u << 16); }
; __device__ __forceinline__ float bfhi(unsigned u) { return __uint_as_float(u & 0xffff0000u); }
; __device__ __forceinline__ float tanhf_(float x) { return 1.f - 2.f * __builtin_amdgcn_rcpf(1.f + __expf(2.f * x)); }
; __device__ __forceinline__ void phase_gemm5(const Params& p, int wid_s, char* shm) {
;     ...
;           for (int j = 0; j < 4; ++j) {
;             int r = ai * 128 + rbase + m * 16 + j;
;             bool doit = (r >= 1 || seq_first) && (r <= 254 || seq_last);
;             if (doit) {
;               unsigned gp = (r >= 1) ? *(const unsigned*)(gs_ + (r - 1) * 130 + cl) : 0u;
;               unsigned gn = (r <= 254) ? *(const unsigned*)(gs_ + (r + 1) * 130 + cl) : 0u;
;               float u0 = cw0.x * bflo(gp) + cw1.x * acc[ai][0][m][0][j] + cw2.x * bflo(gn) + cbv.x;
;               float u1 = cw0.y * bfhi(gp) + cw1.y * acc[ai][0][m][1][j] + cw2.y * bfhi(gn) + cbv.y;
;               float i0 = 0.7978845608028654f * (u0 + 0.044715f * u0 * u0 * u0);
;               float i1 = 0.7978845608028654f * (u1 + 0.044715f * u1 * u1 * u1);
;               float g0 = 0.5f * u0 * (1.f + tanhf_(i0));
;               float g1 = 0.5f * u1 * (1.f + tanhf_(i1));
;               *(unsigned*)(ACT + (size_t)(brow + r) * 5504 + f) = pack2(g0 * acc[ai][1][m][0][j], g1 * acc[ai][1][m][1][j]);
;             }
.LBB0_1104:
	s_or_b64 exec, exec, s[60:61]
	s_movk_i32 s53, 0xef
	v_cmp_lt_i32_e64 s[0:1], -16, v130
	v_cmp_gt_i32_e32 vcc, s53, v130
	s_or_b64 s[60:61], s[0:1], s[56:57]
	s_or_b64 s[62:63], vcc, s[58:59]
	s_and_b64 s[62:63], s[60:61], s[62:63]
	s_and_saveexec_b64 s[60:61], s[62:63]
	s_cbranch_execz .LBB0_1110
	v_mov_b32_e32 v84, 0
	v_mov_b32_e32 v85, 0
	s_and_saveexec_b64 s[62:63], s[0:1]
	v_add3_u32 v85, v181, v156, s92
	ds_read_b32 v85, v85
	s_or_b64 exec, exec, s[62:63]
	s_and_saveexec_b64 s[0:1], vcc
	v_lshl_add_u32 v84, v155, 1, v181
	ds_read_b32 v84, v84 offset:260
	s_or_b64 exec, exec, s[0:1]
	s_waitcnt lgkmcnt(0)
	v_lshlrev_b32_e32 v86, 16, v85
	v_and_b32_e32 v87, 0xffff0000, v85
	v_lshlrev_b32_e32 v88, 16, v84
	v_and_b32_e32 v89, 0xffff0000, v84
	s_waitcnt vmcnt(3)
	v_pk_mul_f32 v[84:85], v[108:109], v[86:87]
	s_waitcnt vmcnt(2)
	v_pk_fma_f32 v[84:85], v[140:141], v[110:111], v[84:85]
	s_waitcnt vmcnt(1)
	v_pk_fma_f32 v[84:85], v[104:105], v[88:89], v[84:85]
	s_waitcnt vmcnt(0)
	v_pk_add_f32 v[84:85], v[106:107], v[84:85]
	s_nop 0
	v_mul_f32_e32 v86, 0x3d372713, v84
	v_mul_f32_e32 v87, 0x3d372713, v85
	v_mul_f32_e32 v86, v84, v86
	v_mul_f32_e32 v87, v85, v87
	v_fma_f32 v86, v84, v86, v84
	v_fma_f32 v87, v85, v87, v85
	v_mul_f32_e32 v86, 0x3f4c422a, v86
	v_mul_f32_e32 v87, 0x3f4c422a, v87
	v_add_f32_e32 v86, v86, v86
	v_add_f32_e32 v87, v87, v87
	v_mul_f32_e32 v86, 0x3fb8aa3b, v86
	v_mul_f32_e32 v87, 0x3fb8aa3b, v87
	v_exp_f32_e32 v86, v86
	v_exp_f32_e32 v87, v87
	v_pk_mul_f32 v[84:85], v[84:85], 0.5 op_sel_hi:[1,0]
	v_add_f32_e32 v86, 1.0, v86
	v_add_f32_e32 v87, 1.0, v87
	v_rcp_f32_e32 v86, v86
	v_rcp_f32_e32 v87, v87
	s_nop 0
	v_pk_fma_f32 v[86:87], v[86:87], -2.0, 1.0 op_sel_hi:[1,0,0]
	s_nop 0
	v_pk_add_f32 v[86:87], v[86:87], 1.0 op_sel_hi:[1,0]
	s_nop 0
	v_pk_mul_f32 v[84:85], v[84:85], v[86:87]
	v_mov_b32_e32 v86, v72
	v_mov_b32_e32 v87, v76
	v_pk_mul_f32 v[84:85], v[86:87], v[84:85]
	v_add3_u32 v76, v130, s54, 16
	v_cvt_pk_bf16_f32 v72, v84, v85
	v_mad_i64_i32 v[84:85], s[0:1], v76, s87, v[98:99]
	global_store_dword v[84:85], v72, off
.LBB0_1110:
	s_or_b64 exec, exec, s[60:61]
	s_movk_i32 s0, 0xffef
	s_movk_i32 s53, 0xee
	v_cmp_lt_i32_e64 s[0:1], s0, v130
	v_cmp_gt_i32_e32 vcc, s53, v130
	s_or_b64 s[60:61], s[0:1], s[56:57]
	s_or_b64 s[62:63], vcc, s[58:59]
	s_and_b64 s[62:63], s[60:61], s[62:63]
	s_and_saveexec_b64 s[60:61], s[62:63]
	s_cbranch_execz .LBB0_1116
	v_mov_b32_e32 v72, 0
	v_mov_b32_e32 v76, 0
	s_and_saveexec_b64 s[62:63], s[0:1]
	v_add3_u32 v76, v180, v156, s92
	ds_read_b32 v76, v76
	s_or_b64 exec, exec, s[62:63]
	s_and_saveexec_b64 s[0:1], vcc
	v_lshl_add_u32 v72, v155, 1, v180
	ds_read_b32 v72, v72 offset:260
	s_or_b64 exec, exec, s[0:1]
	s_waitcnt lgkmcnt(0)
	v_lshlrev_b32_e32 v84, 16, v76
	v_and_b32_e32 v85, 0xffff0000, v76
	s_waitcnt vmcnt(3)
	v_pk_mul_f32 v[84:85], v[108:109], v[84:85]
	v_lshlrev_b32_e32 v86, 16, v72
	v_and_b32_e32 v87, 0xffff0000, v72
	s_waitcnt vmcnt(2)
	v_pk_fma_f32 v[80:81], v[80:81], v[110:111], v[84:85]
	s_waitcnt vmcnt(1)
	v_pk_fma_f32 v[80:81], v[104:105], v[86:87], v[80:81]
	s_waitcnt vmcnt(0)
	v_pk_add_f32 v[80:81], v[106:107], v[80:81]
	s_nop 0
	v_mul_f32_e32 v72, 0x3d372713, v80
	v_mul_f32_e32 v72, v80, v72
	v_mul_f32_e32 v76, 0x3d372713, v81
	v_fma_f32 v72, v80, v72, v80
	v_mul_f32_e32 v76, v81, v76
	v_mul_f32_e32 v72, 0x3f4c422a, v72
	v_fma_f32 v76, v81, v76, v81
	v_mul_f32_e32 v76, 0x3f4c422a, v76
	v_add_f32_e32 v72, v72, v72
	v_mul_f32_e32 v72, 0x3fb8aa3b, v72
	v_add_f32_e32 v76, v76, v76
	v_exp_f32_e32 v72, v72
	v_mul_f32_e32 v76, 0x3fb8aa3b, v76
	v_exp_f32_e32 v76, v76
	v_pk_mul_f32 v[80:81], v[80:81], 0.5 op_sel_hi:[1,0]
	v_add_f32_e32 v72, 1.0, v72
	v_rcp_f32_e32 v84, v72
	v_add_f32_e32 v72, 1.0, v76
	v_rcp_f32_e32 v85, v72
	v_mov_b32_e32 v76, v73
	v_pk_fma_f32 v[84:85], v[84:85], -2.0, 1.0 op_sel_hi:[1,0,0]
	s_nop 0
	v_pk_add_f32 v[84:85], v[84:85], 1.0 op_sel_hi:[1,0]
	s_nop 0
	v_pk_mul_f32 v[80:81], v[80:81], v[84:85]
	s_nop 0
	v_pk_mul_f32 v[72:73], v[76:77], v[80:81]
	s_nop 0
	v_cvt_pk_bf16_f32 v76, v72, v73
	v_add3_u32 v72, v130, s54, 17
	v_mad_i64_i32 v[72:73], s[0:1], v72, s87, v[98:99]
	global_store_dword v[72:73], v76, off
.LBB0_1116:
	s_or_b64 exec, exec, s[60:61]
	s_movk_i32 s0, 0xffee
	s_movk_i32 s53, 0xed
	v_cmp_lt_i32_e64 s[0:1], s0, v130
	v_cmp_gt_i32_e32 vcc, s53, v130
	s_or_b64 s[60:61], s[0:1], s[56:57]
	s_or_b64 s[62:63], vcc, s[58:59]
	s_and_b64 s[62:63], s[60:61], s[62:63]
	s_and_saveexec_b64 s[60:61], s[62:63]
	s_cbranch_execz .LBB0_1122
	v_mov_b32_e32 v72, 0
	v_mov_b32_e32 v73, 0
	s_and_saveexec_b64 s[62:63], s[0:1]
	v_add3_u32 v73, v179, v156, s92
	ds_read_b32 v73, v73
	s_or_b64 exec, exec, s[62:63]
	s_and_saveexec_b64 s[0:1], vcc
	v_lshl_add_u32 v72, v155, 1, v179
	ds_read_b32 v72, v72 offset:260
	s_or_b64 exec, exec, s[0:1]
	s_waitcnt lgkmcnt(0)
	v_lshlrev_b32_e32 v76, 16, v73
	v_and_b32_e32 v77, 0xffff0000, v73
	v_lshlrev_b32_e32 v80, 16, v72
	v_and_b32_e32 v81, 0xffff0000, v72
	s_waitcnt vmcnt(3)
	v_pk_mul_f32 v[72:73], v[108:109], v[76:77]
	s_waitcnt vmcnt(2)
	v_pk_fma_f32 v[72:73], v[138:139], v[110:111], v[72:73]
	s_waitcnt vmcnt(1)
	v_pk_fma_f32 v[72:73], v[104:105], v[80:81], v[72:73]
	s_waitcnt vmcnt(0)
	v_pk_add_f32 v[72:73], v[106:107], v[72:73]
	s_nop 0
	v_mul_f32_e32 v76, 0x3d372713, v72
	v_mul_f32_e32 v77, 0x3d372713, v73
	v_mul_f32_e32 v76, v72, v76
	v_mul_f32_e32 v77, v73, v77
	v_fma_f32 v76, v72, v76, v72
	v_fma_f32 v77, v73, v77, v73
	v_mul_f32_e32 v76, 0x3f4c422a, v76
	v_mul_f32_e32 v77, 0x3f4c422a, v77
	v_add_f32_e32 v76, v76, v76
	v_add_f32_e32 v77, v77, v77
	v_mul_f32_e32 v76, 0x3fb8aa3b, v76
	v_mul_f32_e32 v77, 0x3fb8aa3b, v77
	v_exp_f32_e32 v76, v76
	v_exp_f32_e32 v77, v77
	v_pk_mul_f32 v[72:73], v[72:73], 0.5 op_sel_hi:[1,0]
	v_add_f32_e32 v76, 1.0, v76
	v_add_f32_e32 v77, 1.0, v77
	v_rcp_f32_e32 v76, v76
	v_rcp_f32_e32 v77, v77
	s_nop 0
	v_pk_fma_f32 v[76:77], v[76:77], -2.0, 1.0 op_sel_hi:[1,0,0]
	s_nop 0
	v_pk_add_f32 v[76:77], v[76:77], 1.0 op_sel_hi:[1,0]
	s_nop 0
	v_pk_mul_f32 v[72:73], v[72:73], v[76:77]
	v_mov_b32_e32 v76, v74
	v_mov_b32_e32 v77, v78
	v_pk_mul_f32 v[72:73], v[76:77], v[72:73]
	s_nop 0
	v_cvt_pk_bf16_f32 v74, v72, v73
	v_add3_u32 v72, v130, s54, 18
	v_mad_i64_i32 v[72:73], s[0:1], v72, s87, v[98:99]
	global_store_dword v[72:73], v74, off
; __device__ __forceinline__ float bflo(unsigned u) { return __uint_as_float(u << 16); }
; __device__ __forceinline__ float bfhi(unsigned u) { return __uint_as_float(u & 0xffff0000u); }
; __device__ __forceinline__ float tanhf_(float x) { return 1.f - 2.f * __builtin_amdgcn_rcpf(1.f + __expf(2.f * x)); }
; __device__ __forceinline__ void phase_gemm5(const Params& p, int wid_s, char* shm) {
;     ...
;           for (int j = 0; j < 4; ++j) {
;             int r = ai * 128 + rbase + m * 16 + j;
;             bool doit = (r >= 1 || seq_first) && (r <= 254 || seq_last);
;             if (doit) {
;               unsigned gp = (r >= 1) ? *(const unsigned*)(gs_ + (r - 1) * 130 + cl) : 0u;
;               unsigned gn = (r <= 254) ? *(const unsigned*)(gs_ + (r + 1) * 130 + cl) : 0u;
;               float u0 = cw0.x * bflo(gp) + cw1.x * acc[ai][0][m][0][j] + cw2.x * bflo(gn) + cbv.x;
;               float u1 = cw0.y * bfhi(gp) + cw1.y * acc[ai][0][m][1][j] + cw2.y * bfhi(gn) + cbv.y;
;               float i0 = 0.7978845608028654f * (u0 + 0.044715f * u0 * u0 * u0);
;               float i1 = 0.7978845608028654f * (u1 + 0.044715f * u1 * u1 * u1);
;               float g0 = 0.5f * u0 * (1.f + tanhf_(i0));
;               float g1 = 0.5f * u1 * (1.f + tanhf_(i1));
;               *(unsigned*)(ACT + (size_t)(brow + r) * 5504 + f) = pack2(g0 * acc[ai][1][m][0][j], g1 * acc[ai][1][m][1][j]);
;             }
.LBB0_1122:
	s_or_b64 exec, exec, s[60:61]
	s_movk_i32 s0, 0xffed
	s_movk_i32 s53, 0xec
	v_cmp_lt_i32_e64 s[0:1], s0, v130
	v_cmp_gt_i32_e32 vcc, s53, v130
	s_or_b64 s[60:61], s[0:1], s[56:57]
	s_or_b64 s[62:63], vcc, s[58:59]
	s_and_b64 s[62:63], s[60:61], s[62:63]
	s_and_saveexec_b64 s[60:61], s[62:63]
	s_cbranch_execz .LBB0_1128
	v_mov_b32_e32 v72, 0
	v_mov_b32_e32 v73, 0
	s_and_saveexec_b64 s[62:63], s[0:1]
	v_add3_u32 v73, v178, v156, s92
	ds_read_b32 v73, v73
	s_or_b64 exec, exec, s[62:63]
	s_and_saveexec_b64 s[0:1], vcc
	v_lshl_add_u32 v72, v155, 1, v178
	ds_read_b32 v72, v72 offset:260
	s_or_b64 exec, exec, s[0:1]
	s_waitcnt lgkmcnt(0)
	v_lshlrev_b32_e32 v76, 16, v73
	v_and_b32_e32 v77, 0xffff0000, v73
	v_lshlrev_b32_e32 v80, 16, v72
	v_and_b32_e32 v81, 0xffff0000, v72
	s_waitcnt vmcnt(3)
	v_pk_mul_f32 v[72:73], v[108:109], v[76:77]
	v_mov_b32_e32 v78, v75
	s_waitcnt vmcnt(2)
	v_pk_fma_f32 v[72:73], v[82:83], v[110:111], v[72:73]
	s_waitcnt vmcnt(1)
	v_pk_fma_f32 v[72:73], v[104:105], v[80:81], v[72:73]
	s_waitcnt vmcnt(0)
	v_pk_add_f32 v[72:73], v[106:107], v[72:73]
	s_nop 0
	v_mul_f32_e32 v74, 0x3d372713, v72
	v_mul_f32_e32 v74, v72, v74
	v_mul_f32_e32 v76, 0x3d372713, v73
	v_fma_f32 v74, v72, v74, v72
	v_mul_f32_e32 v76, v73, v76
	v_mul_f32_e32 v74, 0x3f4c422a, v74
	v_fma_f32 v76, v73, v76, v73
	v_mul_f32_e32 v76, 0x3f4c422a, v76
	v_add_f32_e32 v74, v74, v74
	v_mul_f32_e32 v74, 0x3fb8aa3b, v74
	v_add_f32_e32 v76, v76, v76
	v_exp_f32_e32 v74, v74
	v_mul_f32_e32 v76, 0x3fb8aa3b, v76
	v_exp_f32_e32 v77, v76
	v_pk_mul_f32 v[72:73], v[72:73], 0.5 op_sel_hi:[1,0]
	v_add_f32_e32 v74, 1.0, v74
	v_rcp_f32_e32 v76, v74
	v_add_f32_e32 v74, 1.0, v77
	v_rcp_f32_e32 v77, v74
	s_nop 0
	v_pk_fma_f32 v[76:77], v[76:77], -2.0, 1.0 op_sel_hi:[1,0,0]
	s_nop 0
	v_pk_add_f32 v[76:77], v[76:77], 1.0 op_sel_hi:[1,0]
	s_nop 0
	v_pk_mul_f32 v[72:73], v[72:73], v[76:77]
	s_nop 0
	v_pk_mul_f32 v[72:73], v[78:79], v[72:73]
	s_nop 0
	v_cvt_pk_bf16_f32 v74, v72, v73
	v_add3_u32 v72, v130, s54, 19
	v_mad_i64_i32 v[72:73], s[0:1], v72, s87, v[98:99]
	global_store_dword v[72:73], v74, off
.LBB0_1128:
	s_or_b64 exec, exec, s[60:61]
	s_movk_i32 s0, 0xffe0
	s_movk_i32 s53, 0xdf
	v_cmp_lt_i32_e64 s[0:1], s0, v130
	v_cmp_gt_i32_e32 vcc, s53, v130
	s_or_b64 s[60:61], s[0:1], s[56:57]
	s_or_b64 s[62:63], vcc, s[58:59]
	s_and_b64 s[62:63], s[60:61], s[62:63]
	s_and_saveexec_b64 s[60:61], s[62:63]
	s_cbranch_execz .LBB0_1134
	v_mov_b32_e32 v72, 0
	v_mov_b32_e32 v73, 0
	s_and_saveexec_b64 s[62:63], s[0:1]
	v_add3_u32 v73, v177, v156, s92
	ds_read_b32 v73, v73
	s_or_b64 exec, exec, s[62:63]
	s_and_saveexec_b64 s[0:1], vcc
	v_lshl_add_u32 v72, v155, 1, v177
	ds_read_b32 v72, v72 offset:260
	s_or_b64 exec, exec, s[0:1]
	s_waitcnt lgkmcnt(0)
	v_lshlrev_b32_e32 v74, 16, v73
	v_and_b32_e32 v75, 0xffff0000, v73
	v_lshlrev_b32_e32 v76, 16, v72
	v_and_b32_e32 v77, 0xffff0000, v72
	s_waitcnt vmcnt(3)
	v_pk_mul_f32 v[72:73], v[108:109], v[74:75]
	s_waitcnt vmcnt(2)
	v_pk_fma_f32 v[72:73], v[136:137], v[110:111], v[72:73]
	s_waitcnt vmcnt(1)
	v_pk_fma_f32 v[72:73], v[104:105], v[76:77], v[72:73]
	s_waitcnt vmcnt(0)
	v_pk_add_f32 v[72:73], v[106:107], v[72:73]
	s_nop 0
	v_mul_f32_e32 v74, 0x3d372713, v72
	v_mul_f32_e32 v75, 0x3d372713, v73
	v_mul_f32_e32 v74, v72, v74
	v_mul_f32_e32 v75, v73, v75
	v_fma_f32 v74, v72, v74, v72
	v_fma_f32 v75, v73, v75, v73
	v_mul_f32_e32 v74, 0x3f4c422a, v74
	v_mul_f32_e32 v75, 0x3f4c422a, v75
	v_add_f32_e32 v74, v74, v74
	v_add_f32_e32 v75, v75, v75
	v_mul_f32_e32 v74, 0x3fb8aa3b, v74
	v_mul_f32_e32 v75, 0x3fb8aa3b, v75
	v_exp_f32_e32 v74, v74
	v_exp_f32_e32 v75, v75
	v_pk_mul_f32 v[72:73], v[72:73], 0.5 op_sel_hi:[1,0]
	v_add_f32_e32 v74, 1.0, v74
	v_add_f32_e32 v75, 1.0, v75
	v_rcp_f32_e32 v74, v74
	v_rcp_f32_e32 v75, v75
	s_nop 0
	v_pk_fma_f32 v[74:75], v[74:75], -2.0, 1.0 op_sel_hi:[1,0,0]
	s_nop 0
	v_pk_add_f32 v[74:75], v[74:75], 1.0 op_sel_hi:[1,0]
	s_nop 0
	v_pk_mul_f32 v[72:73], v[72:73], v[74:75]
	v_mov_b32_e32 v74, v60
	v_mov_b32_e32 v75, v64
	v_pk_mul_f32 v[72:73], v[74:75], v[72:73]
	v_add3_u32 v64, v130, s54, 32
	v_cvt_pk_bf16_f32 v60, v72, v73
	v_mad_i64_i32 v[72:73], s[0:1], v64, s87, v[98:99]
	global_store_dword v[72:73], v60, off
.LBB0_1134:
	s_or_b64 exec, exec, s[60:61]
	s_movk_i32 s0, 0xffdf
	s_movk_i32 s53, 0xde
	v_cmp_lt_i32_e64 s[0:1], s0, v130
	v_cmp_gt_i32_e32 vcc, s53, v130
	s_or_b64 s[60:61], s[0:1], s[56:57]
	s_or_b64 s[62:63], vcc, s[58:59]
	s_and_b64 s[62:63], s[60:61], s[62:63]
	s_and_saveexec_b64 s[60:61], s[62:63]
	s_cbranch_execz .LBB0_1140
	v_mov_b32_e32 v60, 0
	v_mov_b32_e32 v64, 0
	s_and_saveexec_b64 s[62:63], s[0:1]
	v_add3_u32 v64, v176, v156, s92
	ds_read_b32 v64, v64
	s_or_b64 exec, exec, s[62:63]
	s_and_saveexec_b64 s[0:1], vcc
	v_lshl_add_u32 v60, v155, 1, v176
	ds_read_b32 v60, v60 offset:260
	s_or_b64 exec, exec, s[0:1]
	s_waitcnt lgkmcnt(0)
	v_lshlrev_b32_e32 v72, 16, v64
	v_and_b32_e32 v73, 0xffff0000, v64
	s_waitcnt vmcnt(3)
	v_pk_mul_f32 v[72:73], v[108:109], v[72:73]
	v_lshlrev_b32_e32 v74, 16, v60
	v_and_b32_e32 v75, 0xffff0000, v60
	s_waitcnt vmcnt(2)
	v_pk_fma_f32 v[68:69], v[68:69], v[110:111], v[72:73]
	s_waitcnt vmcnt(1)
	v_pk_fma_f32 v[68:69], v[104:105], v[74:75], v[68:69]
	s_waitcnt vmcnt(0)
	v_pk_add_f32 v[68:69], v[106:107], v[68:69]
	s_nop 0
	v_mul_f32_e32 v60, 0x3d372713, v68
	v_mul_f32_e32 v60, v68, v60
	v_mul_f32_e32 v64, 0x3d372713, v69
	v_fma_f32 v60, v68, v60, v68
	v_mul_f32_e32 v64, v69, v64
	v_mul_f32_e32 v60, 0x3f4c422a, v60
	v_fma_f32 v64, v69, v64, v69
	v_mul_f32_e32 v64, 0x3f4c422a, v64
	v_add_f32_e32 v60, v60, v60
	v_mul_f32_e32 v60, 0x3fb8aa3b, v60
	v_add_f32_e32 v64, v64, v64
	v_exp_f32_e32 v60, v60
	v_mul_f32_e32 v64, 0x3fb8aa3b, v64
	v_exp_f32_e32 v64, v64
	v_pk_mul_f32 v[68:69], v[68:69], 0.5 op_sel_hi:[1,0]
	v_add_f32_e32 v60, 1.0, v60
	v_rcp_f32_e32 v72, v60
	v_add_f32_e32 v60, 1.0, v64
	v_rcp_f32_e32 v73, v60
	v_mov_b32_e32 v64, v61
	v_pk_fma_f32 v[72:73], v[72:73], -2.0, 1.0 op_sel_hi:[1,0,0]
	s_nop 0
	v_pk_add_f32 v[72:73], v[72:73], 1.0 op_sel_hi:[1,0]
	s_nop 0
	v_pk_mul_f32 v[68:69], v[68:69], v[72:73]
	s_nop 0
	v_pk_mul_f32 v[60:61], v[64:65], v[68:69]
	s_nop 0
	v_cvt_pk_bf16_f32 v64, v60, v61
	v_add3_u32 v60, v130, s54, 33
	v_mad_i64_i32 v[60:61], s[0:1], v60, s87, v[98:99]
	global_store_dword v[60:61], v64, off
; __device__ __forceinline__ float bflo(unsigned u) { return __uint_as_float(u << 16); }
; __device__ __forceinline__ float bfhi(unsigned u) { return __uint_as_float(u & 0xffff0000u); }
; __device__ __forceinline__ float tanhf_(float x) { return 1.f - 2.f * __builtin_amdgcn_rcpf(1.f + __expf(2.f * x)); }
; __device__ __forceinline__ void phase_gemm5(const Params& p, int wid_s, char* shm) {
;     ...
;           for (int j = 0; j < 4; ++j) {
;             int r = ai * 128 + rbase + m * 16 + j;
;             bool doit = (r >= 1 || seq_first) && (r <= 254 || seq_last);
;             if (doit) {
;               unsigned gp = (r >= 1) ? *(const unsigned*)(gs_ + (r - 1) * 130 + cl) : 0u;
;               unsigned gn = (r <= 254) ? *(const unsigned*)(gs_ + (r + 1) * 130 + cl) : 0u;
;               float u0 = cw0.x * bflo(gp) + cw1.x * acc[ai][0][m][0][j] + cw2.x * bflo(gn) + cbv.x;
;               float u1 = cw0.y * bfhi(gp) + cw1.y * acc[ai][0][m][1][j] + cw2.y * bfhi(gn) + cbv.y;
;               float i0 = 0.7978845608028654f * (u0 + 0.044715f * u0 * u0 * u0);
;               float i1 = 0.7978845608028654f * (u1 + 0.044715f * u1 * u1 * u1);
;               float g0 = 0.5f * u0 * (1.f + tanhf_(i0));
;               float g1 = 0.5f * u1 * (1.f + tanhf_(i1));
;               *(unsigned*)(ACT + (size_t)(brow + r) * 5504 + f) = pack2(g0 * acc[ai][1][m][0][j], g1 * acc[ai][1][m][1][j]);
;             }
.LBB0_1140:
	s_or_b64 exec, exec, s[60:61]
	s_movk_i32 s0, 0xffde
	s_movk_i32 s53, 0xdd
	v_cmp_lt_i32_e64 s[0:1], s0, v130
	v_cmp_gt_i32_e32 vcc, s53, v130
	s_or_b64 s[60:61], s[0:1], s[56:57]
	s_or_b64 s[62:63], vcc, s[58:59]
	s_and_b64 s[62:63], s[60:61], s[62:63]
	s_and_saveexec_b64 s[60:61], s[62:63]
	s_cbranch_execz .LBB0_1146
	v_mov_b32_e32 v60, 0
	v_mov_b32_e32 v61, 0
	s_and_saveexec_b64 s[62:63], s[0:1]
	v_add3_u32 v61, v175, v156, s92
	ds_read_b32 v61, v61
	s_or_b64 exec, exec, s[62:63]
	s_and_saveexec_b64 s[0:1], vcc
	v_lshl_add_u32 v60, v155, 1, v175
	ds_read_b32 v60, v60 offset:260
	s_or_b64 exec, exec, s[0:1]
	s_waitcnt lgkmcnt(0)
	v_lshlrev_b32_e32 v64, 16, v61
	v_and_b32_e32 v65, 0xffff0000, v61
	v_lshlrev_b32_e32 v68, 16, v60
	v_and_b32_e32 v69, 0xffff0000, v60
	s_waitcnt vmcnt(3)
	v_pk_mul_f32 v[60:61], v[108:109], v[64:65]
	s_waitcnt vmcnt(2)
	v_pk_fma_f32 v[60:61], v[134:135], v[110:111], v[60:61]
	s_waitcnt vmcnt(1)
	v_pk_fma_f32 v[60:61], v[104:105], v[68:69], v[60:61]
	s_waitcnt vmcnt(0)
	v_pk_add_f32 v[60:61], v[106:107], v[60:61]
	s_nop 0
	v_mul_f32_e32 v64, 0x3d372713, v60
	v_mul_f32_e32 v65, 0x3d372713, v61
	v_mul_f32_e32 v64, v60, v64
	v_mul_f32_e32 v65, v61, v65
	v_fma_f32 v64, v60, v64, v60
	v_fma_f32 v65, v61, v65, v61
	v_mul_f32_e32 v64, 0x3f4c422a, v64
	v_mul_f32_e32 v65, 0x3f4c422a, v65
	v_add_f32_e32 v64, v64, v64
	v_add_f32_e32 v65, v65, v65
	v_mul_f32_e32 v64, 0x3fb8aa3b, v64
	v_mul_f32_e32 v65, 0x3fb8aa3b, v65
	v_exp_f32_e32 v64, v64
	v_exp_f32_e32 v65, v65
	v_pk_mul_f32 v[60:61], v[60:61], 0.5 op_sel_hi:[1,0]
	v_add_f32_e32 v64, 1.0, v64
	v_add_f32_e32 v65, 1.0, v65
	v_rcp_f32_e32 v64, v64
	v_rcp_f32_e32 v65, v65
	s_nop 0
	v_pk_fma_f32 v[64:65], v[64:65], -2.0, 1.0 op_sel_hi:[1,0,0]
	s_nop 0
	v_pk_add_f32 v[64:65], v[64:65], 1.0 op_sel_hi:[1,0]
	s_nop 0
	v_pk_mul_f32 v[60:61], v[60:61], v[64:65]
	v_mov_b32_e32 v64, v62
	v_mov_b32_e32 v65, v66
	v_pk_mul_f32 v[60:61], v[64:65], v[60:61]
	s_nop 0
	v_cvt_pk_bf16_f32 v62, v60, v61
	v_add3_u32 v60, v130, s54, 34
	v_mad_i64_i32 v[60:61], s[0:1], v60, s87, v[98:99]
	global_store_dword v[60:61], v62, off
.LBB0_1146:
	s_or_b64 exec, exec, s[60:61]
	s_movk_i32 s0, 0xffdd
	s_movk_i32 s53, 0xdc
	v_cmp_lt_i32_e64 s[0:1], s0, v130
	v_cmp_gt_i32_e32 vcc, s53, v130
	s_or_b64 s[60:61], s[0:1], s[56:57]
	s_or_b64 s[62:63], vcc, s[58:59]
	s_and_b64 s[62:63], s[60:61], s[62:63]
	s_and_saveexec_b64 s[60:61], s[62:63]
	s_cbranch_execz .LBB0_1152
	v_mov_b32_e32 v60, 0
	v_mov_b32_e32 v61, 0
	s_and_saveexec_b64 s[62:63], s[0:1]
	v_add3_u32 v61, v174, v156, s92
	ds_read_b32 v61, v61
	s_or_b64 exec, exec, s[62:63]
	s_and_saveexec_b64 s[0:1], vcc
	v_lshl_add_u32 v60, v155, 1, v174
	ds_read_b32 v60, v60 offset:260
	s_or_b64 exec, exec, s[0:1]
	s_waitcnt lgkmcnt(0)
	v_lshlrev_b32_e32 v64, 16, v61
	v_and_b32_e32 v65, 0xffff0000, v61
	v_lshlrev_b32_e32 v68, 16, v60
	v_and_b32_e32 v69, 0xffff0000, v60
	s_waitcnt vmcnt(3)
	v_pk_mul_f32 v[60:61], v[108:109], v[64:65]
	v_mov_b32_e32 v66, v63
	s_waitcnt vmcnt(2)
	v_pk_fma_f32 v[60:61], v[70:71], v[110:111], v[60:61]
	s_waitcnt vmcnt(1)
	v_pk_fma_f32 v[60:61], v[104:105], v[68:69], v[60:61]
	s_waitcnt vmcnt(0)
	v_pk_add_f32 v[60:61], v[106:107], v[60:61]
	s_nop 0
	v_mul_f32_e32 v62, 0x3d372713, v60
	v_mul_f32_e32 v62, v60, v62
	v_mul_f32_e32 v64, 0x3d372713, v61
	v_fma_f32 v62, v60, v62, v60
	v_mul_f32_e32 v64, v61, v64
	v_mul_f32_e32 v62, 0x3f4c422a, v62
	v_fma_f32 v64, v61, v64, v61
	v_mul_f32_e32 v64, 0x3f4c422a, v64
	v_add_f32_e32 v62, v62, v62
	v_mul_f32_e32 v62, 0x3fb8aa3b, v62
	v_add_f32_e32 v64, v64, v64
	v_exp_f32_e32 v62, v62
	v_mul_f32_e32 v64, 0x3fb8aa3b, v64
	v_exp_f32_e32 v65, v64
	v_pk_mul_f32 v[60:61], v[60:61], 0.5 op_sel_hi:[1,0]
	v_add_f32_e32 v62, 1.0, v62
	v_rcp_f32_e32 v64, v62
	v_add_f32_e32 v62, 1.0, v65
	v_rcp_f32_e32 v65, v62
	s_nop 0
	v_pk_fma_f32 v[64:65], v[64:65], -2.0, 1.0 op_sel_hi:[1,0,0]
	s_nop 0
	v_pk_add_f32 v[64:65], v[64:65], 1.0 op_sel_hi:[1,0]
	s_nop 0
	v_pk_mul_f32 v[60:61], v[60:61], v[64:65]
	s_nop 0
	v_pk_mul_f32 v[60:61], v[66:67], v[60:61]
	s_nop 0
	v_cvt_pk_bf16_f32 v62, v60, v61
	v_add3_u32 v60, v130, s54, 35
	v_mad_i64_i32 v[60:61], s[0:1], v60, s87, v[98:99]
	global_store_dword v[60:61], v62, off
.LBB0_1152:
	s_or_b64 exec, exec, s[60:61]
	s_movk_i32 s0, 0xffd0
	s_movk_i32 s53, 0xcf
	v_cmp_lt_i32_e64 s[0:1], s0, v130
	v_cmp_gt_i32_e32 vcc, s53, v130
	s_or_b64 s[60:61], s[0:1], s[56:57]
	s_or_b64 s[62:63], vcc, s[58:59]
	s_and_b64 s[62:63], s[60:61], s[62:63]
	s_and_saveexec_b64 s[60:61], s[62:63]
	s_cbranch_execz .LBB0_1158
	v_mov_b32_e32 v60, 0
	v_mov_b32_e32 v61, 0
	s_and_saveexec_b64 s[62:63], s[0:1]
	v_add3_u32 v61, v173, v156, s92
	ds_read_b32 v61, v61
	s_or_b64 exec, exec, s[62:63]
	s_and_saveexec_b64 s[0:1], vcc
	v_lshl_add_u32 v60, v155, 1, v173
	ds_read_b32 v60, v60 offset:260
	s_or_b64 exec, exec, s[0:1]
	s_waitcnt lgkmcnt(0)
	v_lshlrev_b32_e32 v62, 16, v61
	v_and_b32_e32 v63, 0xffff0000, v61
	v_lshlrev_b32_e32 v64, 16, v60
	v_and_b32_e32 v65, 0xffff0000, v60
	s_waitcnt vmcnt(3)
	v_pk_mul_f32 v[60:61], v[108:109], v[62:63]
	s_waitcnt vmcnt(2)
	v_pk_fma_f32 v[60:61], v[132:133], v[110:111], v[60:61]
	s_waitcnt vmcnt(1)
	v_pk_fma_f32 v[60:61], v[104:105], v[64:65], v[60:61]
	s_waitcnt vmcnt(0)
	v_pk_add_f32 v[60:61], v[106:107], v[60:61]
	s_nop 0
	v_mul_f32_e32 v62, 0x3d372713, v60
	v_mul_f32_e32 v63, 0x3d372713, v61
	v_mul_f32_e32 v62, v60, v62
	v_mul_f32_e32 v63, v61, v63
	v_fma_f32 v62, v60, v62, v60
	v_fma_f32 v63, v61, v63, v61
	v_mul_f32_e32 v62, 0x3f4c422a, v62
	v_mul_f32_e32 v63, 0x3f4c422a, v63
	v_add_f32_e32 v62, v62, v62
	v_add_f32_e32 v63, v63, v63
	v_mul_f32_e32 v62, 0x3fb8aa3b, v62
	v_mul_f32_e32 v63, 0x3fb8aa3b, v63
	v_exp_f32_e32 v62, v62
	v_exp_f32_e32 v63, v63
	v_pk_mul_f32 v[60:61], v[60:61], 0.5 op_sel_hi:[1,0]
	v_add_f32_e32 v62, 1.0, v62
	v_add_f32_e32 v63, 1.0, v63
	v_rcp_f32_e32 v62, v62
	v_rcp_f32_e32 v63, v63
	s_nop 0
	v_pk_fma_f32 v[62:63], v[62:63], -2.0, 1.0 op_sel_hi:[1,0,0]
	s_nop 0
	v_pk_add_f32 v[62:63], v[62:63], 1.0 op_sel_hi:[1,0]
	s_nop 0
	v_pk_mul_f32 v[60:61], v[60:61], v[62:63]
	v_mov_b32_e32 v62, v48
	v_mov_b32_e32 v63, v52
	v_pk_mul_f32 v[60:61], v[62:63], v[60:61]
	v_add3_u32 v52, v130, s54, 48
	v_cvt_pk_bf16_f32 v48, v60, v61
	v_mad_i64_i32 v[60:61], s[0:1], v52, s87, v[98:99]
	global_store_dword v[60:61], v48, off
; __device__ __forceinline__ float bflo(unsigned u) { return __uint_as_float(u << 16); }
; __device__ __forceinline__ float bfhi(unsigned u) { return __uint_as_float(u & 0xffff0000u); }
; __device__ __forceinline__ float tanhf_(float x) { return 1.f - 2.f * __builtin_amdgcn_rcpf(1.f + __expf(2.f * x)); }
; __device__ __forceinline__ void phase_gemm5(const Params& p, int wid_s, char* shm) {
;     ...
;           for (int j = 0; j < 4; ++j) {
;             int r = ai * 128 + rbase + m * 16 + j;
;             bool doit = (r >= 1 || seq_first) && (r <= 254 || seq_last);
;             if (doit) {
;               unsigned gp = (r >= 1) ? *(const unsigned*)(gs_ + (r - 1) * 130 + cl) : 0u;
;               unsigned gn = (r <= 254) ? *(const unsigned*)(gs_ + (r + 1) * 130 + cl) : 0u;
;               float u0 = cw0.x * bflo(gp) + cw1.x * acc[ai][0][m][0][j] + cw2.x * bflo(gn) + cbv.x;
;               float u1 = cw0.y * bfhi(gp) + cw1.y * acc[ai][0][m][1][j] + cw2.y * bfhi(gn) + cbv.y;
;               float i0 = 0.7978845608028654f * (u0 + 0.044715f * u0 * u0 * u0);
;               float i1 = 0.7978845608028654f * (u1 + 0.044715f * u1 * u1 * u1);
;               float g0 = 0.5f * u0 * (1.f + tanhf_(i0));
;               float g1 = 0.5f * u1 * (1.f + tanhf_(i1));
;               *(unsigned*)(ACT + (size_t)(brow + r) * 5504 + f) = pack2(g0 * acc[ai][1][m][0][j], g1 * acc[ai][1][m][1][j]);
;             }
.LBB0_1158:
	s_or_b64 exec, exec, s[60:61]
	s_movk_i32 s0, 0xffcf
	s_movk_i32 s53, 0xce
	v_cmp_lt_i32_e64 s[0:1], s0, v130
	v_cmp_gt_i32_e32 vcc, s53, v130
	s_or_b64 s[60:61], s[0:1], s[56:57]
	s_or_b64 s[62:63], vcc, s[58:59]
	s_and_b64 s[62:63], s[60:61], s[62:63]
	s_and_saveexec_b64 s[60:61], s[62:63]
	s_cbranch_execz .LBB0_1164
	v_mov_b32_e32 v48, 0
	v_mov_b32_e32 v52, 0
	s_and_saveexec_b64 s[62:63], s[0:1]
	v_add3_u32 v52, v172, v156, s92
	ds_read_b32 v52, v52
	s_or_b64 exec, exec, s[62:63]
	s_and_saveexec_b64 s[0:1], vcc
	v_lshl_add_u32 v48, v155, 1, v172
	ds_read_b32 v48, v48 offset:260
	s_or_b64 exec, exec, s[0:1]
	s_waitcnt lgkmcnt(0)
	v_lshlrev_b32_e32 v60, 16, v52
	v_and_b32_e32 v61, 0xffff0000, v52
	s_waitcnt vmcnt(3)
	v_pk_mul_f32 v[60:61], v[108:109], v[60:61]
	v_lshlrev_b32_e32 v62, 16, v48
	v_and_b32_e32 v63, 0xffff0000, v48
	s_waitcnt vmcnt(2)
	v_pk_fma_f32 v[56:57], v[56:57], v[110:111], v[60:61]
	s_waitcnt vmcnt(1)
	v_pk_fma_f32 v[56:57], v[104:105], v[62:63], v[56:57]
	s_waitcnt vmcnt(0)
	v_pk_add_f32 v[56:57], v[106:107], v[56:57]
	s_nop 0
	v_mul_f32_e32 v48, 0x3d372713, v56
	v_mul_f32_e32 v48, v56, v48
	v_mul_f32_e32 v52, 0x3d372713, v57
	v_fma_f32 v48, v56, v48, v56
	v_mul_f32_e32 v52, v57, v52
	v_mul_f32_e32 v48, 0x3f4c422a, v48
	v_fma_f32 v52, v57, v52, v57
	v_mul_f32_e32 v52, 0x3f4c422a, v52
	v_add_f32_e32 v48, v48, v48
	v_mul_f32_e32 v48, 0x3fb8aa3b, v48
	v_add_f32_e32 v52, v52, v52
	v_exp_f32_e32 v48, v48
	v_mul_f32_e32 v52, 0x3fb8aa3b, v52
	v_exp_f32_e32 v52, v52
	v_pk_mul_f32 v[56:57], v[56:57], 0.5 op_sel_hi:[1,0]
	v_add_f32_e32 v48, 1.0, v48
	v_rcp_f32_e32 v60, v48
	v_add_f32_e32 v48, 1.0, v52
	v_rcp_f32_e32 v61, v48
	v_mov_b32_e32 v52, v49
	v_pk_fma_f32 v[60:61], v[60:61], -2.0, 1.0 op_sel_hi:[1,0,0]
	s_nop 0
	v_pk_add_f32 v[60:61], v[60:61], 1.0 op_sel_hi:[1,0]
	s_nop 0
	v_pk_mul_f32 v[56:57], v[56:57], v[60:61]
	s_nop 0
	v_pk_mul_f32 v[48:49], v[52:53], v[56:57]
	s_nop 0
	v_cvt_pk_bf16_f32 v52, v48, v49
	v_add3_u32 v48, v130, s54, 49
	v_mad_i64_i32 v[48:49], s[0:1], v48, s87, v[98:99]
	global_store_dword v[48:49], v52, off
.LBB0_1164:
	s_or_b64 exec, exec, s[60:61]
	s_movk_i32 s0, 0xffce
	s_movk_i32 s53, 0xcd
	v_cmp_lt_i32_e64 s[0:1], s0, v130
	v_cmp_gt_i32_e32 vcc, s53, v130
	s_or_b64 s[60:61], s[0:1], s[56:57]
	s_or_b64 s[62:63], vcc, s[58:59]
	s_and_b64 s[62:63], s[60:61], s[62:63]
	s_and_saveexec_b64 s[60:61], s[62:63]
	s_cbranch_execz .LBB0_1170
	v_mov_b32_e32 v48, 0
	v_mov_b32_e32 v49, 0
	s_and_saveexec_b64 s[62:63], s[0:1]
	v_add3_u32 v49, v171, v156, s92
	ds_read_b32 v49, v49
	s_or_b64 exec, exec, s[62:63]
	s_and_saveexec_b64 s[0:1], vcc
	v_lshl_add_u32 v48, v155, 1, v171
	ds_read_b32 v48, v48 offset:260
	s_or_b64 exec, exec, s[0:1]
	s_waitcnt lgkmcnt(0)
	v_lshlrev_b32_e32 v52, 16, v49
	v_and_b32_e32 v53, 0xffff0000, v49
	v_lshlrev_b32_e32 v56, 16, v48
	v_and_b32_e32 v57, 0xffff0000, v48
	s_waitcnt vmcnt(3)
	v_pk_mul_f32 v[48:49], v[108:109], v[52:53]
	s_waitcnt vmcnt(2)
	v_pk_fma_f32 v[48:49], v[126:127], v[110:111], v[48:49]
	s_waitcnt vmcnt(1)
	v_pk_fma_f32 v[48:49], v[104:105], v[56:57], v[48:49]
	s_waitcnt vmcnt(0)
	v_pk_add_f32 v[48:49], v[106:107], v[48:49]
	s_nop 0
	v_mul_f32_e32 v52, 0x3d372713, v48
	v_mul_f32_e32 v53, 0x3d372713, v49
	v_mul_f32_e32 v52, v48, v52
	v_mul_f32_e32 v53, v49, v53
	v_fma_f32 v52, v48, v52, v48
	v_fma_f32 v53, v49, v53, v49
	v_mul_f32_e32 v52, 0x3f4c422a, v52
	v_mul_f32_e32 v53, 0x3f4c422a, v53
	v_add_f32_e32 v52, v52, v52
	v_add_f32_e32 v53, v53, v53
	v_mul_f32_e32 v52, 0x3fb8aa3b, v52
	v_mul_f32_e32 v53, 0x3fb8aa3b, v53
	v_exp_f32_e32 v52, v52
	v_exp_f32_e32 v53, v53
	v_pk_mul_f32 v[48:49], v[48:49], 0.5 op_sel_hi:[1,0]
	v_add_f32_e32 v52, 1.0, v52
	v_add_f32_e32 v53, 1.0, v53
	v_rcp_f32_e32 v52, v52
	v_rcp_f32_e32 v53, v53
	s_nop 0
	v_pk_fma_f32 v[52:53], v[52:53], -2.0, 1.0 op_sel_hi:[1,0,0]
	s_nop 0
	v_pk_add_f32 v[52:53], v[52:53], 1.0 op_sel_hi:[1,0]
	s_nop 0
	v_pk_mul_f32 v[48:49], v[48:49], v[52:53]
	v_mov_b32_e32 v52, v50
	v_mov_b32_e32 v53, v54
	v_pk_mul_f32 v[48:49], v[52:53], v[48:49]
	s_nop 0
	v_cvt_pk_bf16_f32 v50, v48, v49
	v_add3_u32 v48, v130, s54, 50
	v_mad_i64_i32 v[48:49], s[0:1], v48, s87, v[98:99]
	global_store_dword v[48:49], v50, off
.LBB0_1170:
	s_or_b64 exec, exec, s[60:61]
	s_movk_i32 s0, 0xffcd
	s_movk_i32 s53, 0xcc
	v_cmp_lt_i32_e64 s[0:1], s0, v130
	v_cmp_gt_i32_e32 vcc, s53, v130
	s_or_b64 s[60:61], s[0:1], s[56:57]
	s_or_b64 s[62:63], vcc, s[58:59]
	s_and_b64 s[62:63], s[60:61], s[62:63]
	s_and_saveexec_b64 s[60:61], s[62:63]
	s_cbranch_execz .LBB0_1176
	v_mov_b32_e32 v48, 0
	v_mov_b32_e32 v49, 0
	s_and_saveexec_b64 s[62:63], s[0:1]
	v_add3_u32 v49, v170, v156, s92
	ds_read_b32 v49, v49
	s_or_b64 exec, exec, s[62:63]
	s_and_saveexec_b64 s[0:1], vcc
	v_lshl_add_u32 v48, v155, 1, v170
	ds_read_b32 v48, v48 offset:260
	s_or_b64 exec, exec, s[0:1]
	s_waitcnt lgkmcnt(0)
	v_lshlrev_b32_e32 v52, 16, v49
	v_and_b32_e32 v53, 0xffff0000, v49
	v_lshlrev_b32_e32 v56, 16, v48
	v_and_b32_e32 v57, 0xffff0000, v48
	s_waitcnt vmcnt(3)
	v_pk_mul_f32 v[48:49], v[108:109], v[52:53]
	v_mov_b32_e32 v54, v51
	s_waitcnt vmcnt(2)
	v_pk_fma_f32 v[48:49], v[58:59], v[110:111], v[48:49]
	s_waitcnt vmcnt(1)
	v_pk_fma_f32 v[48:49], v[104:105], v[56:57], v[48:49]
	s_waitcnt vmcnt(0)
	v_pk_add_f32 v[48:49], v[106:107], v[48:49]
	s_nop 0
	v_mul_f32_e32 v50, 0x3d372713, v48
	v_mul_f32_e32 v50, v48, v50
	v_mul_f32_e32 v52, 0x3d372713, v49
	v_fma_f32 v50, v48, v50, v48
	v_mul_f32_e32 v52, v49, v52
	v_mul_f32_e32 v50, 0x3f4c422a, v50
	v_fma_f32 v52, v49, v52, v49
	v_mul_f32_e32 v52, 0x3f4c422a, v52
	v_add_f32_e32 v50, v50, v50
	v_mul_f32_e32 v50, 0x3fb8aa3b, v50
	v_add_f32_e32 v52, v52, v52
	v_exp_f32_e32 v50, v50
	v_mul_f32_e32 v52, 0x3fb8aa3b, v52
	v_exp_f32_e32 v53, v52
	v_pk_mul_f32 v[48:49], v[48:49], 0.5 op_sel_hi:[1,0]
	v_add_f32_e32 v50, 1.0, v50
	v_rcp_f32_e32 v52, v50
	v_add_f32_e32 v50, 1.0, v53
	v_rcp_f32_e32 v53, v50
	s_nop 0
	v_pk_fma_f32 v[52:53], v[52:53], -2.0, 1.0 op_sel_hi:[1,0,0]
	s_nop 0
	v_pk_add_f32 v[52:53], v[52:53], 1.0 op_sel_hi:[1,0]
	s_nop 0
	v_pk_mul_f32 v[48:49], v[48:49], v[52:53]
	s_nop 0
	v_pk_mul_f32 v[48:49], v[54:55], v[48:49]
	s_nop 0
	v_cvt_pk_bf16_f32 v50, v48, v49
	v_add3_u32 v48, v130, s54, 51
	v_mad_i64_i32 v[48:49], s[0:1], v48, s87, v[98:99]
	global_store_dword v[48:49], v50, off
; __device__ __forceinline__ float bflo(unsigned u) { return __uint_as_float(u << 16); }
; __device__ __forceinline__ float bfhi(unsigned u) { return __uint_as_float(u & 0xffff0000u); }
; __device__ __forceinline__ float tanhf_(float x) { return 1.f - 2.f * __builtin_amdgcn_rcpf(1.f + __expf(2.f * x)); }
; __device__ __forceinline__ void phase_gemm5(const Params& p, int wid_s, char* shm) {
;     ...
;           for (int j = 0; j < 4; ++j) {
;             int r = ai * 128 + rbase + m * 16 + j;
;             bool doit = (r >= 1 || seq_first) && (r <= 254 || seq_last);
;             if (doit) {
;               unsigned gp = (r >= 1) ? *(const unsigned*)(gs_ + (r - 1) * 130 + cl) : 0u;
;               unsigned gn = (r <= 254) ? *(const unsigned*)(gs_ + (r + 1) * 130 + cl) : 0u;
;               float u0 = cw0.x * bflo(gp) + cw1.x * acc[ai][0][m][0][j] + cw2.x * bflo(gn) + cbv.x;
;               float u1 = cw0.y * bfhi(gp) + cw1.y * acc[ai][0][m][1][j] + cw2.y * bfhi(gn) + cbv.y;
;               float i0 = 0.7978845608028654f * (u0 + 0.044715f * u0 * u0 * u0);
;               float i1 = 0.7978845608028654f * (u1 + 0.044715f * u1 * u1 * u1);
;               float g0 = 0.5f * u0 * (1.f + tanhf_(i0));
;               float g1 = 0.5f * u1 * (1.f + tanhf_(i1));
;               *(unsigned*)(ACT + (size_t)(brow + r) * 5504 + f) = pack2(g0 * acc[ai][1][m][0][j], g1 * acc[ai][1][m][1][j]);
;             }
.LBB0_1176:
	s_or_b64 exec, exec, s[60:61]
	s_movk_i32 s0, 0xff80
	s_movk_i32 s53, 0x7f
	v_cmp_lt_i32_e64 s[0:1], s0, v130
	v_cmp_gt_i32_e32 vcc, s53, v130
	s_or_b64 s[60:61], s[0:1], s[56:57]
	s_or_b64 s[62:63], vcc, s[58:59]
	s_and_b64 s[62:63], s[60:61], s[62:63]
	s_and_saveexec_b64 s[60:61], s[62:63]
	s_cbranch_execz .LBB0_1182
	v_mov_b32_e32 v48, 0
	v_mov_b32_e32 v49, 0
	s_and_saveexec_b64 s[62:63], s[0:1]
	v_add3_u32 v49, v169, v156, s92
	ds_read_b32 v49, v49
	s_or_b64 exec, exec, s[62:63]
	s_and_saveexec_b64 s[0:1], vcc
	v_lshl_add_u32 v48, v155, 1, v169
	ds_read_b32 v48, v48 offset:260
	s_or_b64 exec, exec, s[0:1]
	s_waitcnt lgkmcnt(0)
	v_lshlrev_b32_e32 v50, 16, v49
	v_and_b32_e32 v51, 0xffff0000, v49
	v_lshlrev_b32_e32 v52, 16, v48
	v_and_b32_e32 v53, 0xffff0000, v48
	s_waitcnt vmcnt(3)
	v_pk_mul_f32 v[48:49], v[108:109], v[50:51]
	s_waitcnt vmcnt(2)
	v_pk_fma_f32 v[48:49], v[124:125], v[110:111], v[48:49]
	s_waitcnt vmcnt(1)
	v_pk_fma_f32 v[48:49], v[104:105], v[52:53], v[48:49]
	v_add_u32_e32 v52, s54, v130
	s_waitcnt vmcnt(0)
	v_pk_add_f32 v[48:49], v[106:107], v[48:49]
	s_nop 0
	v_mul_f32_e32 v50, 0x3d372713, v48
	v_mul_f32_e32 v51, 0x3d372713, v49
	v_mul_f32_e32 v50, v48, v50
	v_mul_f32_e32 v51, v49, v51
	v_fma_f32 v50, v48, v50, v48
	v_fma_f32 v51, v49, v51, v49
	v_mul_f32_e32 v50, 0x3f4c422a, v50
	v_mul_f32_e32 v51, 0x3f4c422a, v51
	v_add_f32_e32 v50, v50, v50
	v_add_f32_e32 v51, v51, v51
	v_mul_f32_e32 v50, 0x3fb8aa3b, v50
	v_mul_f32_e32 v51, 0x3fb8aa3b, v51
	v_exp_f32_e32 v50, v50
	v_exp_f32_e32 v51, v51
	v_pk_mul_f32 v[48:49], v[48:49], 0.5 op_sel_hi:[1,0]
	v_add_f32_e32 v50, 1.0, v50
	v_add_f32_e32 v51, 1.0, v51
	v_rcp_f32_e32 v50, v50
	v_rcp_f32_e32 v51, v51
	s_nop 0
	v_pk_fma_f32 v[50:51], v[50:51], -2.0, 1.0 op_sel_hi:[1,0,0]
	s_nop 0
	v_pk_add_f32 v[50:51], v[50:51], 1.0 op_sel_hi:[1,0]
	s_nop 0
	v_pk_mul_f32 v[48:49], v[48:49], v[50:51]
	v_mov_b32_e32 v50, v36
	v_mov_b32_e32 v51, v40
	v_pk_mul_f32 v[48:49], v[50:51], v[48:49]
	v_add_u32_e32 v40, 0x80, v52
	v_cvt_pk_bf16_f32 v36, v48, v49
	v_mad_i64_i32 v[48:49], s[0:1], v40, s87, v[98:99]
	global_store_dword v[48:49], v36, off
.LBB0_1182:
	s_or_b64 exec, exec, s[60:61]
	s_movk_i32 s0, 0xff7f
	s_movk_i32 s53, 0x7e
	v_cmp_lt_i32_e64 s[0:1], s0, v130
	v_cmp_gt_i32_e32 vcc, s53, v130
	s_or_b64 s[60:61], s[0:1], s[56:57]
	s_or_b64 s[62:63], vcc, s[58:59]
	s_and_b64 s[62:63], s[60:61], s[62:63]
	s_and_saveexec_b64 s[60:61], s[62:63]
	s_cbranch_execz .LBB0_1188
	v_mov_b32_e32 v36, 0
	v_mov_b32_e32 v40, 0
	s_and_saveexec_b64 s[62:63], s[0:1]
	v_add3_u32 v40, v168, v156, s92
	ds_read_b32 v40, v40
	s_or_b64 exec, exec, s[62:63]
	s_and_saveexec_b64 s[0:1], vcc
	v_lshl_add_u32 v36, v155, 1, v168
	ds_read_b32 v36, v36 offset:260
	s_or_b64 exec, exec, s[0:1]
	s_waitcnt lgkmcnt(0)
	v_lshlrev_b32_e32 v48, 16, v40
	v_and_b32_e32 v49, 0xffff0000, v40
	s_waitcnt vmcnt(3)
	v_pk_mul_f32 v[48:49], v[108:109], v[48:49]
	v_lshlrev_b32_e32 v50, 16, v36
	v_and_b32_e32 v51, 0xffff0000, v36
	s_waitcnt vmcnt(2)
	v_pk_fma_f32 v[44:45], v[44:45], v[110:111], v[48:49]
	s_waitcnt vmcnt(1)
	v_pk_fma_f32 v[44:45], v[104:105], v[50:51], v[44:45]
	v_add_u32_e32 v50, s54, v130
	s_waitcnt vmcnt(0)
	v_pk_add_f32 v[44:45], v[106:107], v[44:45]
	s_nop 0
	v_mul_f32_e32 v36, 0x3d372713, v44
	v_mul_f32_e32 v36, v44, v36
	v_mul_f32_e32 v40, 0x3d372713, v45
	v_fma_f32 v36, v44, v36, v44
	v_mul_f32_e32 v40, v45, v40
	v_mul_f32_e32 v36, 0x3f4c422a, v36
	v_fma_f32 v40, v45, v40, v45
	v_mul_f32_e32 v40, 0x3f4c422a, v40
	v_add_f32_e32 v36, v36, v36
	v_mul_f32_e32 v36, 0x3fb8aa3b, v36
	v_add_f32_e32 v40, v40, v40
	v_exp_f32_e32 v36, v36
	v_mul_f32_e32 v40, 0x3fb8aa3b, v40
	v_exp_f32_e32 v40, v40
	v_pk_mul_f32 v[44:45], v[44:45], 0.5 op_sel_hi:[1,0]
	v_add_f32_e32 v36, 1.0, v36
	v_rcp_f32_e32 v48, v36
	v_add_f32_e32 v36, 1.0, v40
	v_rcp_f32_e32 v49, v36
	v_mov_b32_e32 v40, v37
	v_pk_fma_f32 v[48:49], v[48:49], -2.0, 1.0 op_sel_hi:[1,0,0]
	s_nop 0
	v_pk_add_f32 v[48:49], v[48:49], 1.0 op_sel_hi:[1,0]
	s_nop 0
	v_pk_mul_f32 v[44:45], v[44:45], v[48:49]
	s_nop 0
	v_pk_mul_f32 v[36:37], v[40:41], v[44:45]
	s_nop 0
	v_cvt_pk_bf16_f32 v40, v36, v37
	v_add_u32_e32 v36, 0x81, v50
	v_mad_i64_i32 v[36:37], s[0:1], v36, s87, v[98:99]
	global_store_dword v[36:37], v40, off
.LBB0_1188:
	s_or_b64 exec, exec, s[60:61]
	s_movk_i32 s0, 0xff7e
	s_movk_i32 s53, 0x7d
	v_cmp_lt_i32_e64 s[0:1], s0, v130
	v_cmp_gt_i32_e32 vcc, s53, v130
	s_or_b64 s[60:61], s[0:1], s[56:57]
	s_or_b64 s[62:63], vcc, s[58:59]
	s_and_b64 s[62:63], s[60:61], s[62:63]
	s_and_saveexec_b64 s[60:61], s[62:63]
	s_cbranch_execz .LBB0_1194
	v_mov_b32_e32 v36, 0
	v_mov_b32_e32 v37, 0
	s_and_saveexec_b64 s[62:63], s[0:1]
	v_add3_u32 v37, v167, v156, s92
	ds_read_b32 v37, v37
	s_or_b64 exec, exec, s[62:63]
	s_and_saveexec_b64 s[0:1], vcc
	v_lshl_add_u32 v36, v155, 1, v167
	ds_read_b32 v36, v36 offset:260
	s_or_b64 exec, exec, s[0:1]
	s_waitcnt lgkmcnt(0)
	v_lshlrev_b32_e32 v40, 16, v37
	v_and_b32_e32 v41, 0xffff0000, v37
	v_lshlrev_b32_e32 v44, 16, v36
	v_and_b32_e32 v45, 0xffff0000, v36
	s_waitcnt vmcnt(3)
	v_pk_mul_f32 v[36:37], v[108:109], v[40:41]
	s_waitcnt vmcnt(2)
	v_pk_fma_f32 v[36:37], v[122:123], v[110:111], v[36:37]
	s_waitcnt vmcnt(1)
	v_pk_fma_f32 v[36:37], v[104:105], v[44:45], v[36:37]
	v_add_u32_e32 v44, s54, v130
	s_waitcnt vmcnt(0)
	v_pk_add_f32 v[36:37], v[106:107], v[36:37]
	s_nop 0
	v_mul_f32_e32 v40, 0x3d372713, v36
	v_mul_f32_e32 v41, 0x3d372713, v37
	v_mul_f32_e32 v40, v36, v40
	v_mul_f32_e32 v41, v37, v41
	v_fma_f32 v40, v36, v40, v36
	v_fma_f32 v41, v37, v41, v37
	v_mul_f32_e32 v40, 0x3f4c422a, v40
	v_mul_f32_e32 v41, 0x3f4c422a, v41
	v_add_f32_e32 v40, v40, v40
	v_add_f32_e32 v41, v41, v41
	v_mul_f32_e32 v40, 0x3fb8aa3b, v40
	v_mul_f32_e32 v41, 0x3fb8aa3b, v41
	v_exp_f32_e32 v40, v40
	v_exp_f32_e32 v41, v41
	v_pk_mul_f32 v[36:37], v[36:37], 0.5 op_sel_hi:[1,0]
	v_add_f32_e32 v40, 1.0, v40
	v_add_f32_e32 v41, 1.0, v41
	v_rcp_f32_e32 v40, v40
	v_rcp_f32_e32 v41, v41
	s_nop 0
	v_pk_fma_f32 v[40:41], v[40:41], -2.0, 1.0 op_sel_hi:[1,0,0]
	s_nop 0
	v_pk_add_f32 v[40:41], v[40:41], 1.0 op_sel_hi:[1,0]
	s_nop 0
	v_pk_mul_f32 v[36:37], v[36:37], v[40:41]
	v_mov_b32_e32 v40, v38
	v_mov_b32_e32 v41, v42
	v_pk_mul_f32 v[36:37], v[40:41], v[36:37]
	s_nop 0
	v_cvt_pk_bf16_f32 v38, v36, v37
	v_add_u32_e32 v36, 0x82, v44
	v_mad_i64_i32 v[36:37], s[0:1], v36, s87, v[98:99]
	global_store_dword v[36:37], v38, off
; __device__ __forceinline__ float bflo(unsigned u) { return __uint_as_float(u << 16); }
; __device__ __forceinline__ float bfhi(unsigned u) { return __uint_as_float(u & 0xffff0000u); }
; __device__ __forceinline__ float tanhf_(float x) { return 1.f - 2.f * __builtin_amdgcn_rcpf(1.f + __expf(2.f * x)); }
; __device__ __forceinline__ void phase_gemm5(const Params& p, int wid_s, char* shm) {
;     ...
;           for (int j = 0; j < 4; ++j) {
;             int r = ai * 128 + rbase + m * 16 + j;
;             bool doit = (r >= 1 || seq_first) && (r <= 254 || seq_last);
;             if (doit) {
;               unsigned gp = (r >= 1) ? *(const unsigned*)(gs_ + (r - 1) * 130 + cl) : 0u;
;               unsigned gn = (r <= 254) ? *(const unsigned*)(gs_ + (r + 1) * 130 + cl) : 0u;
;               float u0 = cw0.x * bflo(gp) + cw1.x * acc[ai][0][m][0][j] + cw2.x * bflo(gn) + cbv.x;
;               float u1 = cw0.y * bfhi(gp) + cw1.y * acc[ai][0][m][1][j] + cw2.y * bfhi(gn) + cbv.y;
;               float i0 = 0.7978845608028654f * (u0 + 0.044715f * u0 * u0 * u0);
;               float i1 = 0.7978845608028654f * (u1 + 0.044715f * u1 * u1 * u1);
;               float g0 = 0.5f * u0 * (1.f + tanhf_(i0));
;               float g1 = 0.5f * u1 * (1.f + tanhf_(i1));
;               *(unsigned*)(ACT + (size_t)(brow + r) * 5504 + f) = pack2(g0 * acc[ai][1][m][0][j], g1 * acc[ai][1][m][1][j]);
;             }
.LBB0_1194:
	s_or_b64 exec, exec, s[60:61]
	s_movk_i32 s0, 0xff7d
	s_movk_i32 s53, 0x7c
	v_cmp_lt_i32_e64 s[0:1], s0, v130
	v_cmp_gt_i32_e32 vcc, s53, v130
	s_or_b64 s[60:61], s[0:1], s[56:57]
	s_or_b64 s[62:63], vcc, s[58:59]
	s_and_b64 s[62:63], s[60:61], s[62:63]
	s_and_saveexec_b64 s[60:61], s[62:63]
	s_cbranch_execz .LBB0_1200
	v_mov_b32_e32 v36, 0
	v_mov_b32_e32 v37, 0
	s_and_saveexec_b64 s[62:63], s[0:1]
	v_add3_u32 v37, v166, v156, s92
	ds_read_b32 v37, v37
	s_or_b64 exec, exec, s[62:63]
	s_and_saveexec_b64 s[0:1], vcc
	v_lshl_add_u32 v36, v155, 1, v166
	ds_read_b32 v36, v36 offset:260
	s_or_b64 exec, exec, s[0:1]
	s_waitcnt lgkmcnt(0)
	v_lshlrev_b32_e32 v40, 16, v37
	v_and_b32_e32 v41, 0xffff0000, v37
	v_lshlrev_b32_e32 v44, 16, v36
	v_and_b32_e32 v45, 0xffff0000, v36
	s_waitcnt vmcnt(3)
	v_pk_mul_f32 v[36:37], v[108:109], v[40:41]
	v_mov_b32_e32 v42, v39
	s_waitcnt vmcnt(2)
	v_pk_fma_f32 v[36:37], v[46:47], v[110:111], v[36:37]
	s_waitcnt vmcnt(1)
	v_pk_fma_f32 v[36:37], v[104:105], v[44:45], v[36:37]
	s_waitcnt vmcnt(0)
	v_pk_add_f32 v[36:37], v[106:107], v[36:37]
	s_nop 0
	v_mul_f32_e32 v38, 0x3d372713, v36
	v_mul_f32_e32 v38, v36, v38
	v_mul_f32_e32 v40, 0x3d372713, v37
	v_fma_f32 v38, v36, v38, v36
	v_mul_f32_e32 v40, v37, v40
	v_mul_f32_e32 v38, 0x3f4c422a, v38
	v_fma_f32 v40, v37, v40, v37
	v_mul_f32_e32 v40, 0x3f4c422a, v40
	v_add_f32_e32 v38, v38, v38
	v_mul_f32_e32 v38, 0x3fb8aa3b, v38
	v_add_f32_e32 v40, v40, v40
	v_exp_f32_e32 v38, v38
	v_mul_f32_e32 v40, 0x3fb8aa3b, v40
	v_exp_f32_e32 v41, v40
	v_pk_mul_f32 v[36:37], v[36:37], 0.5 op_sel_hi:[1,0]
	v_add_f32_e32 v38, 1.0, v38
	v_rcp_f32_e32 v40, v38
	v_add_f32_e32 v38, 1.0, v41
	v_rcp_f32_e32 v41, v38
	v_add_u32_e32 v38, s54, v130
	v_pk_fma_f32 v[40:41], v[40:41], -2.0, 1.0 op_sel_hi:[1,0,0]
	s_nop 0
	v_pk_add_f32 v[40:41], v[40:41], 1.0 op_sel_hi:[1,0]
	s_nop 0
	v_pk_mul_f32 v[36:37], v[36:37], v[40:41]
	s_nop 0
	v_pk_mul_f32 v[36:37], v[42:43], v[36:37]
	s_nop 0
	v_cvt_pk_bf16_f32 v39, v36, v37
	v_add_u32_e32 v36, 0x83, v38
	v_mad_i64_i32 v[36:37], s[0:1], v36, s87, v[98:99]
	global_store_dword v[36:37], v39, off
.LBB0_1200:
	s_or_b64 exec, exec, s[60:61]
	s_movk_i32 s0, 0xff70
	s_movk_i32 s53, 0x6f
	v_cmp_lt_i32_e64 s[0:1], s0, v130
	v_cmp_gt_i32_e32 vcc, s53, v130
	s_or_b64 s[60:61], s[0:1], s[56:57]
	s_or_b64 s[62:63], vcc, s[58:59]
	s_and_b64 s[62:63], s[60:61], s[62:63]
	s_and_saveexec_b64 s[60:61], s[62:63]
	s_cbranch_execz .LBB0_1206
	v_mov_b32_e32 v36, 0
	v_mov_b32_e32 v37, 0
	s_and_saveexec_b64 s[62:63], s[0:1]
	v_add3_u32 v37, v165, v156, s92
	ds_read_b32 v37, v37
	s_or_b64 exec, exec, s[62:63]
	s_and_saveexec_b64 s[0:1], vcc
	v_lshl_add_u32 v36, v155, 1, v165
	ds_read_b32 v36, v36 offset:260
	s_or_b64 exec, exec, s[0:1]
	s_waitcnt lgkmcnt(0)
	v_lshlrev_b32_e32 v38, 16, v37
	v_and_b32_e32 v39, 0xffff0000, v37
	v_lshlrev_b32_e32 v40, 16, v36
	v_and_b32_e32 v41, 0xffff0000, v36
	s_waitcnt vmcnt(3)
	v_pk_mul_f32 v[36:37], v[108:109], v[38:39]
	s_waitcnt vmcnt(2)
	v_pk_fma_f32 v[36:37], v[120:121], v[110:111], v[36:37]
	s_waitcnt vmcnt(1)
	v_pk_fma_f32 v[36:37], v[104:105], v[40:41], v[36:37]
	v_add_u32_e32 v40, s54, v130
	s_waitcnt vmcnt(0)
	v_pk_add_f32 v[36:37], v[106:107], v[36:37]
	s_nop 0
	v_mul_f32_e32 v38, 0x3d372713, v36
	v_mul_f32_e32 v39, 0x3d372713, v37
	v_mul_f32_e32 v38, v36, v38
	v_mul_f32_e32 v39, v37, v39
	v_fma_f32 v38, v36, v38, v36
	v_fma_f32 v39, v37, v39, v37
	v_mul_f32_e32 v38, 0x3f4c422a, v38
	v_mul_f32_e32 v39, 0x3f4c422a, v39
	v_add_f32_e32 v38, v38, v38
	v_add_f32_e32 v39, v39, v39
	v_mul_f32_e32 v38, 0x3fb8aa3b, v38
	v_mul_f32_e32 v39, 0x3fb8aa3b, v39
	v_exp_f32_e32 v38, v38
	v_exp_f32_e32 v39, v39
	v_pk_mul_f32 v[36:37], v[36:37], 0.5 op_sel_hi:[1,0]
	v_add_f32_e32 v38, 1.0, v38
	v_add_f32_e32 v39, 1.0, v39
	v_rcp_f32_e32 v38, v38
	v_rcp_f32_e32 v39, v39
	s_nop 0
	v_pk_fma_f32 v[38:39], v[38:39], -2.0, 1.0 op_sel_hi:[1,0,0]
	s_nop 0
	v_pk_add_f32 v[38:39], v[38:39], 1.0 op_sel_hi:[1,0]
	s_nop 0
	v_pk_mul_f32 v[36:37], v[36:37], v[38:39]
	v_mov_b32_e32 v38, v24
	v_mov_b32_e32 v39, v28
	v_pk_mul_f32 v[36:37], v[38:39], v[36:37]
	v_add_u32_e32 v28, 0x90, v40
	v_cvt_pk_bf16_f32 v24, v36, v37
	v_mad_i64_i32 v[36:37], s[0:1], v28, s87, v[98:99]
	global_store_dword v[36:37], v24, off
.LBB0_1206:
	s_or_b64 exec, exec, s[60:61]
	s_movk_i32 s0, 0xff6f
	s_movk_i32 s53, 0x6e
	v_cmp_lt_i32_e64 s[0:1], s0, v130
	v_cmp_gt_i32_e32 vcc, s53, v130
	s_or_b64 s[60:61], s[0:1], s[56:57]
	s_or_b64 s[62:63], vcc, s[58:59]
	s_and_b64 s[62:63], s[60:61], s[62:63]
	s_and_saveexec_b64 s[60:61], s[62:63]
	s_cbranch_execz .LBB0_1212
	v_mov_b32_e32 v24, 0
	v_mov_b32_e32 v28, 0
	s_and_saveexec_b64 s[62:63], s[0:1]
	v_add3_u32 v28, v164, v156, s92
	ds_read_b32 v28, v28
	s_or_b64 exec, exec, s[62:63]
	s_and_saveexec_b64 s[0:1], vcc
	v_lshl_add_u32 v24, v155, 1, v164
	ds_read_b32 v24, v24 offset:260
	s_or_b64 exec, exec, s[0:1]
	s_waitcnt lgkmcnt(0)
	v_lshlrev_b32_e32 v36, 16, v28
	v_and_b32_e32 v37, 0xffff0000, v28
	s_waitcnt vmcnt(3)
	v_pk_mul_f32 v[36:37], v[108:109], v[36:37]
	v_lshlrev_b32_e32 v38, 16, v24
	v_and_b32_e32 v39, 0xffff0000, v24
	s_waitcnt vmcnt(2)
	v_pk_fma_f32 v[32:33], v[32:33], v[110:111], v[36:37]
	s_waitcnt vmcnt(1)
	v_pk_fma_f32 v[32:33], v[104:105], v[38:39], v[32:33]
	v_add_u32_e32 v38, s54, v130
	s_waitcnt vmcnt(0)
	v_pk_add_f32 v[32:33], v[106:107], v[32:33]
	s_nop 0
	v_mul_f32_e32 v24, 0x3d372713, v32
	v_mul_f32_e32 v24, v32, v24
	v_mul_f32_e32 v28, 0x3d372713, v33
	v_fma_f32 v24, v32, v24, v32
	v_mul_f32_e32 v28, v33, v28
	v_mul_f32_e32 v24, 0x3f4c422a, v24
	v_fma_f32 v28, v33, v28, v33
	v_mul_f32_e32 v28, 0x3f4c422a, v28
	v_add_f32_e32 v24, v24, v24
	v_mul_f32_e32 v24, 0x3fb8aa3b, v24
	v_add_f32_e32 v28, v28, v28
	v_exp_f32_e32 v24, v24
	v_mul_f32_e32 v28, 0x3fb8aa3b, v28
	v_exp_f32_e32 v28, v28
	v_pk_mul_f32 v[32:33], v[32:33], 0.5 op_sel_hi:[1,0]
	v_add_f32_e32 v24, 1.0, v24
	v_rcp_f32_e32 v36, v24
	v_add_f32_e32 v24, 1.0, v28
	v_rcp_f32_e32 v37, v24
	v_mov_b32_e32 v28, v25
	v_pk_fma_f32 v[36:37], v[36:37], -2.0, 1.0 op_sel_hi:[1,0,0]
	s_nop 0
	v_pk_add_f32 v[36:37], v[36:37], 1.0 op_sel_hi:[1,0]
	s_nop 0
	v_pk_mul_f32 v[32:33], v[32:33], v[36:37]
	s_nop 0
	v_pk_mul_f32 v[24:25], v[28:29], v[32:33]
	s_nop 0
	v_cvt_pk_bf16_f32 v28, v24, v25
	v_add_u32_e32 v24, 0x91, v38
	v_mad_i64_i32 v[24:25], s[0:1], v24, s87, v[98:99]
	global_store_dword v[24:25], v28, off
; __device__ __forceinline__ float bflo(unsigned u) { return __uint_as_float(u << 16); }
; __device__ __forceinline__ float bfhi(unsigned u) { return __uint_as_float(u & 0xffff0000u); }
; __device__ __forceinline__ float tanhf_(float x) { return 1.f - 2.f * __builtin_amdgcn_rcpf(1.f + __expf(2.f * x)); }
; __device__ __forceinline__ void phase_gemm5(const Params& p, int wid_s, char* shm) {
;     ...
;           for (int j = 0; j < 4; ++j) {
;             int r = ai * 128 + rbase + m * 16 + j;
;             bool doit = (r >= 1 || seq_first) && (r <= 254 || seq_last);
;             if (doit) {
;               unsigned gp = (r >= 1) ? *(const unsigned*)(gs_ + (r - 1) * 130 + cl) : 0u;
;               unsigned gn = (r <= 254) ? *(const unsigned*)(gs_ + (r + 1) * 130 + cl) : 0u;
;               float u0 = cw0.x * bflo(gp) + cw1.x * acc[ai][0][m][0][j] + cw2.x * bflo(gn) + cbv.x;
;               float u1 = cw0.y * bfhi(gp) + cw1.y * acc[ai][0][m][1][j] + cw2.y * bfhi(gn) + cbv.y;
;               float i0 = 0.7978845608028654f * (u0 + 0.044715f * u0 * u0 * u0);
;               float i1 = 0.7978845608028654f * (u1 + 0.044715f * u1 * u1 * u1);
;               float g0 = 0.5f * u0 * (1.f + tanhf_(i0));
;               float g1 = 0.5f * u1 * (1.f + tanhf_(i1));
;               *(unsigned*)(ACT + (size_t)(brow + r) * 5504 + f) = pack2(g0 * acc[ai][1][m][0][j], g1 * acc[ai][1][m][1][j]);
;             }
.LBB0_1212:
	s_or_b64 exec, exec, s[60:61]
	s_movk_i32 s0, 0xff6e
	s_movk_i32 s53, 0x6d
	v_cmp_lt_i32_e64 s[0:1], s0, v130
	v_cmp_gt_i32_e32 vcc, s53, v130
	s_or_b64 s[60:61], s[0:1], s[56:57]
	s_or_b64 s[62:63], vcc, s[58:59]
	s_and_b64 s[62:63], s[60:61], s[62:63]
	s_and_saveexec_b64 s[60:61], s[62:63]
	s_cbranch_execz .LBB0_1218
	v_mov_b32_e32 v24, 0
	v_mov_b32_e32 v25, 0
	s_and_saveexec_b64 s[62:63], s[0:1]
	v_add3_u32 v25, v163, v156, s92
	ds_read_b32 v25, v25
	s_or_b64 exec, exec, s[62:63]
	s_and_saveexec_b64 s[0:1], vcc
	v_lshl_add_u32 v24, v155, 1, v163
	ds_read_b32 v24, v24 offset:260
	s_or_b64 exec, exec, s[0:1]
	s_waitcnt lgkmcnt(0)
	v_lshlrev_b32_e32 v28, 16, v25
	v_and_b32_e32 v29, 0xffff0000, v25
	v_lshlrev_b32_e32 v32, 16, v24
	v_and_b32_e32 v33, 0xffff0000, v24
	s_waitcnt vmcnt(3)
	v_pk_mul_f32 v[24:25], v[108:109], v[28:29]
	s_waitcnt vmcnt(2)
	v_pk_fma_f32 v[24:25], v[118:119], v[110:111], v[24:25]
	s_waitcnt vmcnt(1)
	v_pk_fma_f32 v[24:25], v[104:105], v[32:33], v[24:25]
	v_add_u32_e32 v32, s54, v130
	s_waitcnt vmcnt(0)
	v_pk_add_f32 v[24:25], v[106:107], v[24:25]
	s_nop 0
	v_mul_f32_e32 v28, 0x3d372713, v24
	v_mul_f32_e32 v29, 0x3d372713, v25
	v_mul_f32_e32 v28, v24, v28
	v_mul_f32_e32 v29, v25, v29
	v_fma_f32 v28, v24, v28, v24
	v_fma_f32 v29, v25, v29, v25
	v_mul_f32_e32 v28, 0x3f4c422a, v28
	v_mul_f32_e32 v29, 0x3f4c422a, v29
	v_add_f32_e32 v28, v28, v28
	v_add_f32_e32 v29, v29, v29
	v_mul_f32_e32 v28, 0x3fb8aa3b, v28
	v_mul_f32_e32 v29, 0x3fb8aa3b, v29
	v_exp_f32_e32 v28, v28
	v_exp_f32_e32 v29, v29
	v_pk_mul_f32 v[24:25], v[24:25], 0.5 op_sel_hi:[1,0]
	v_add_f32_e32 v28, 1.0, v28
	v_add_f32_e32 v29, 1.0, v29
	v_rcp_f32_e32 v28, v28
	v_rcp_f32_e32 v29, v29
	s_nop 0
	v_pk_fma_f32 v[28:29], v[28:29], -2.0, 1.0 op_sel_hi:[1,0,0]
	s_nop 0
	v_pk_add_f32 v[28:29], v[28:29], 1.0 op_sel_hi:[1,0]
	s_nop 0
	v_pk_mul_f32 v[24:25], v[24:25], v[28:29]
	v_mov_b32_e32 v28, v26
	v_mov_b32_e32 v29, v30
	v_pk_mul_f32 v[24:25], v[28:29], v[24:25]
	s_nop 0
	v_cvt_pk_bf16_f32 v26, v24, v25
	v_add_u32_e32 v24, 0x92, v32
	v_mad_i64_i32 v[24:25], s[0:1], v24, s87, v[98:99]
	global_store_dword v[24:25], v26, off
.LBB0_1218:
	s_or_b64 exec, exec, s[60:61]
	s_movk_i32 s0, 0xff6d
	s_movk_i32 s53, 0x6c
	v_cmp_lt_i32_e64 s[0:1], s0, v130
	v_cmp_gt_i32_e32 vcc, s53, v130
	s_or_b64 s[60:61], s[0:1], s[56:57]
	s_or_b64 s[62:63], vcc, s[58:59]
	s_and_b64 s[62:63], s[60:61], s[62:63]
	s_and_saveexec_b64 s[60:61], s[62:63]
	s_cbranch_execz .LBB0_1224
	v_mov_b32_e32 v24, 0
	v_mov_b32_e32 v25, 0
	s_and_saveexec_b64 s[62:63], s[0:1]
	v_add3_u32 v25, v162, v156, s92
	ds_read_b32 v25, v25
	s_or_b64 exec, exec, s[62:63]
	s_and_saveexec_b64 s[0:1], vcc
	v_lshl_add_u32 v24, v155, 1, v162
	ds_read_b32 v24, v24 offset:260
	s_or_b64 exec, exec, s[0:1]
	s_waitcnt lgkmcnt(0)
	v_lshlrev_b32_e32 v28, 16, v25
	v_and_b32_e32 v29, 0xffff0000, v25
	v_lshlrev_b32_e32 v32, 16, v24
	v_and_b32_e32 v33, 0xffff0000, v24
	s_waitcnt vmcnt(3)
	v_pk_mul_f32 v[24:25], v[108:109], v[28:29]
	v_mov_b32_e32 v30, v27
	s_waitcnt vmcnt(2)
	v_pk_fma_f32 v[24:25], v[34:35], v[110:111], v[24:25]
	s_waitcnt vmcnt(1)
	v_pk_fma_f32 v[24:25], v[104:105], v[32:33], v[24:25]
	s_waitcnt vmcnt(0)
	v_pk_add_f32 v[24:25], v[106:107], v[24:25]
	s_nop 0
	v_mul_f32_e32 v26, 0x3d372713, v24
	v_mul_f32_e32 v26, v24, v26
	v_mul_f32_e32 v28, 0x3d372713, v25
	v_fma_f32 v26, v24, v26, v24
	v_mul_f32_e32 v28, v25, v28
	v_mul_f32_e32 v26, 0x3f4c422a, v26
	v_fma_f32 v28, v25, v28, v25
	v_mul_f32_e32 v28, 0x3f4c422a, v28
	v_add_f32_e32 v26, v26, v26
	v_mul_f32_e32 v26, 0x3fb8aa3b, v26
	v_add_f32_e32 v28, v28, v28
	v_exp_f32_e32 v26, v26
	v_mul_f32_e32 v28, 0x3fb8aa3b, v28
	v_exp_f32_e32 v29, v28
	v_pk_mul_f32 v[24:25], v[24:25], 0.5 op_sel_hi:[1,0]
	v_add_f32_e32 v26, 1.0, v26
	v_rcp_f32_e32 v28, v26
	v_add_f32_e32 v26, 1.0, v29
	v_rcp_f32_e32 v29, v26
	v_add_u32_e32 v26, s54, v130
	v_pk_fma_f32 v[28:29], v[28:29], -2.0, 1.0 op_sel_hi:[1,0,0]
	s_nop 0
	v_pk_add_f32 v[28:29], v[28:29], 1.0 op_sel_hi:[1,0]
	s_nop 0
	v_pk_mul_f32 v[24:25], v[24:25], v[28:29]
	s_nop 0
	v_pk_mul_f32 v[24:25], v[30:31], v[24:25]
	s_nop 0
	v_cvt_pk_bf16_f32 v27, v24, v25
	v_add_u32_e32 v24, 0x93, v26
	v_mad_i64_i32 v[24:25], s[0:1], v24, s87, v[98:99]
	global_store_dword v[24:25], v27, off
.LBB0_1224:
	s_or_b64 exec, exec, s[60:61]
	s_movk_i32 s0, 0xff60
	s_movk_i32 s53, 0x5f
	v_cmp_lt_i32_e64 s[0:1], s0, v130
	v_cmp_gt_i32_e32 vcc, s53, v130
	s_or_b64 s[60:61], s[0:1], s[56:57]
	s_or_b64 s[62:63], vcc, s[58:59]
	s_and_b64 s[62:63], s[60:61], s[62:63]
	s_and_saveexec_b64 s[60:61], s[62:63]
	s_cbranch_execz .LBB0_1230
	v_mov_b32_e32 v24, 0
	v_mov_b32_e32 v25, 0
	s_and_saveexec_b64 s[62:63], s[0:1]
	v_add3_u32 v25, v161, v156, s92
	ds_read_b32 v25, v25
	s_or_b64 exec, exec, s[62:63]
	s_and_saveexec_b64 s[0:1], vcc
	v_lshl_add_u32 v24, v155, 1, v161
	ds_read_b32 v24, v24 offset:260
	s_or_b64 exec, exec, s[0:1]
	s_waitcnt lgkmcnt(0)
	v_lshlrev_b32_e32 v26, 16, v25
	v_and_b32_e32 v27, 0xffff0000, v25
	v_lshlrev_b32_e32 v28, 16, v24
	v_and_b32_e32 v29, 0xffff0000, v24
	s_waitcnt vmcnt(3)
	v_pk_mul_f32 v[24:25], v[108:109], v[26:27]
	s_waitcnt vmcnt(2)
	v_pk_fma_f32 v[24:25], v[116:117], v[110:111], v[24:25]
	s_waitcnt vmcnt(1)
	v_pk_fma_f32 v[24:25], v[104:105], v[28:29], v[24:25]
	v_add_u32_e32 v28, s54, v130
	s_waitcnt vmcnt(0)
	v_pk_add_f32 v[24:25], v[106:107], v[24:25]
	s_nop 0
	v_mul_f32_e32 v26, 0x3d372713, v24
	v_mul_f32_e32 v27, 0x3d372713, v25
	v_mul_f32_e32 v26, v24, v26
	v_mul_f32_e32 v27, v25, v27
	v_fma_f32 v26, v24, v26, v24
	v_fma_f32 v27, v25, v27, v25
	v_mul_f32_e32 v26, 0x3f4c422a, v26
	v_mul_f32_e32 v27, 0x3f4c422a, v27
	v_add_f32_e32 v26, v26, v26
	v_add_f32_e32 v27, v27, v27
	v_mul_f32_e32 v26, 0x3fb8aa3b, v26
	v_mul_f32_e32 v27, 0x3fb8aa3b, v27
	v_exp_f32_e32 v26, v26
	v_exp_f32_e32 v27, v27
	v_pk_mul_f32 v[24:25], v[24:25], 0.5 op_sel_hi:[1,0]
	v_add_f32_e32 v26, 1.0, v26
	v_add_f32_e32 v27, 1.0, v27
	v_rcp_f32_e32 v26, v26
	v_rcp_f32_e32 v27, v27
	s_nop 0
	v_pk_fma_f32 v[26:27], v[26:27], -2.0, 1.0 op_sel_hi:[1,0,0]
	s_nop 0
	v_pk_add_f32 v[26:27], v[26:27], 1.0 op_sel_hi:[1,0]
	s_nop 0
	v_pk_mul_f32 v[24:25], v[24:25], v[26:27]
	v_mov_b32_e32 v26, v12
	v_mov_b32_e32 v27, v16
	v_pk_mul_f32 v[24:25], v[26:27], v[24:25]
	v_add_u32_e32 v16, 0xa0, v28
	v_cvt_pk_bf16_f32 v12, v24, v25
	v_mad_i64_i32 v[24:25], s[0:1], v16, s87, v[98:99]
	global_store_dword v[24:25], v12, off
; __device__ __forceinline__ float bflo(unsigned u) { return __uint_as_float(u << 16); }
; __device__ __forceinline__ float bfhi(unsigned u) { return __uint_as_float(u & 0xffff0000u); }
; __device__ __forceinline__ float tanhf_(float x) { return 1.f - 2.f * __builtin_amdgcn_rcpf(1.f + __expf(2.f * x)); }
; __device__ __forceinline__ void phase_gemm5(const Params& p, int wid_s, char* shm) {
;     ...
;           for (int j = 0; j < 4; ++j) {
;             int r = ai * 128 + rbase + m * 16 + j;
;             bool doit = (r >= 1 || seq_first) && (r <= 254 || seq_last);
;             if (doit) {
;               unsigned gp = (r >= 1) ? *(const unsigned*)(gs_ + (r - 1) * 130 + cl) : 0u;
;               unsigned gn = (r <= 254) ? *(const unsigned*)(gs_ + (r + 1) * 130 + cl) : 0u;
;               float u0 = cw0.x * bflo(gp) + cw1.x * acc[ai][0][m][0][j] + cw2.x * bflo(gn) + cbv.x;
;               float u1 = cw0.y * bfhi(gp) + cw1.y * acc[ai][0][m][1][j] + cw2.y * bfhi(gn) + cbv.y;
;               float i0 = 0.7978845608028654f * (u0 + 0.044715f * u0 * u0 * u0);
;               float i1 = 0.7978845608028654f * (u1 + 0.044715f * u1 * u1 * u1);
;               float g0 = 0.5f * u0 * (1.f + tanhf_(i0));
;               float g1 = 0.5f * u1 * (1.f + tanhf_(i1));
;               *(unsigned*)(ACT + (size_t)(brow + r) * 5504 + f) = pack2(g0 * acc[ai][1][m][0][j], g1 * acc[ai][1][m][1][j]);
;             }
.LBB0_1230:
	s_or_b64 exec, exec, s[60:61]
	s_movk_i32 s0, 0xff5f
	s_movk_i32 s53, 0x5e
	v_cmp_lt_i32_e64 s[0:1], s0, v130
	v_cmp_gt_i32_e32 vcc, s53, v130
	s_or_b64 s[60:61], s[0:1], s[56:57]
	s_or_b64 s[62:63], vcc, s[58:59]
	s_and_b64 s[62:63], s[60:61], s[62:63]
	s_and_saveexec_b64 s[60:61], s[62:63]
	s_cbranch_execz .LBB0_1236
	v_mov_b32_e32 v12, 0
	v_mov_b32_e32 v16, 0
	s_and_saveexec_b64 s[62:63], s[0:1]
	v_add3_u32 v16, v160, v156, s92
	ds_read_b32 v16, v16
	s_or_b64 exec, exec, s[62:63]
	s_and_saveexec_b64 s[0:1], vcc
	v_lshl_add_u32 v12, v155, 1, v160
	ds_read_b32 v12, v12 offset:260
	s_or_b64 exec, exec, s[0:1]
	s_waitcnt lgkmcnt(0)
	v_lshlrev_b32_e32 v24, 16, v16
	v_and_b32_e32 v25, 0xffff0000, v16
	s_waitcnt vmcnt(3)
	v_pk_mul_f32 v[24:25], v[108:109], v[24:25]
	v_lshlrev_b32_e32 v26, 16, v12
	v_and_b32_e32 v27, 0xffff0000, v12
	s_waitcnt vmcnt(2)
	v_pk_fma_f32 v[20:21], v[20:21], v[110:111], v[24:25]
	s_waitcnt vmcnt(1)
	v_pk_fma_f32 v[20:21], v[104:105], v[26:27], v[20:21]
	v_add_u32_e32 v26, s54, v130
	s_waitcnt vmcnt(0)
	v_pk_add_f32 v[20:21], v[106:107], v[20:21]
	s_nop 0
	v_mul_f32_e32 v12, 0x3d372713, v20
	v_mul_f32_e32 v12, v20, v12
	v_mul_f32_e32 v16, 0x3d372713, v21
	v_fma_f32 v12, v20, v12, v20
	v_mul_f32_e32 v16, v21, v16
	v_mul_f32_e32 v12, 0x3f4c422a, v12
	v_fma_f32 v16, v21, v16, v21
	v_mul_f32_e32 v16, 0x3f4c422a, v16
	v_add_f32_e32 v12, v12, v12
	v_mul_f32_e32 v12, 0x3fb8aa3b, v12
	v_add_f32_e32 v16, v16, v16
	v_exp_f32_e32 v12, v12
	v_mul_f32_e32 v16, 0x3fb8aa3b, v16
	v_exp_f32_e32 v16, v16
	v_pk_mul_f32 v[20:21], v[20:21], 0.5 op_sel_hi:[1,0]
	v_add_f32_e32 v12, 1.0, v12
	v_rcp_f32_e32 v24, v12
	v_add_f32_e32 v12, 1.0, v16
	v_rcp_f32_e32 v25, v12
	v_mov_b32_e32 v16, v13
	v_pk_fma_f32 v[24:25], v[24:25], -2.0, 1.0 op_sel_hi:[1,0,0]
	s_nop 0
	v_pk_add_f32 v[24:25], v[24:25], 1.0 op_sel_hi:[1,0]
	s_nop 0
	v_pk_mul_f32 v[20:21], v[20:21], v[24:25]
	s_nop 0
	v_pk_mul_f32 v[12:13], v[16:17], v[20:21]
	s_nop 0
	v_cvt_pk_bf16_f32 v16, v12, v13
	v_add_u32_e32 v12, 0xa1, v26
	v_mad_i64_i32 v[12:13], s[0:1], v12, s87, v[98:99]
	global_store_dword v[12:13], v16, off
.LBB0_1236:
	s_or_b64 exec, exec, s[60:61]
	s_movk_i32 s0, 0xff5e
	s_movk_i32 s53, 0x5d
	v_cmp_lt_i32_e64 s[0:1], s0, v130
	v_cmp_gt_i32_e32 vcc, s53, v130
	s_or_b64 s[60:61], s[0:1], s[56:57]
	s_or_b64 s[62:63], vcc, s[58:59]
	s_and_b64 s[62:63], s[60:61], s[62:63]
	s_and_saveexec_b64 s[60:61], s[62:63]
	s_cbranch_execz .LBB0_1242
	v_mov_b32_e32 v12, 0
	v_mov_b32_e32 v13, 0
	s_and_saveexec_b64 s[62:63], s[0:1]
	v_add3_u32 v13, v159, v156, s92
	ds_read_b32 v13, v13
	s_or_b64 exec, exec, s[62:63]
	s_and_saveexec_b64 s[0:1], vcc
	v_lshl_add_u32 v12, v155, 1, v159
	ds_read_b32 v12, v12 offset:260
	s_or_b64 exec, exec, s[0:1]
	s_waitcnt lgkmcnt(0)
	v_lshlrev_b32_e32 v16, 16, v13
	v_and_b32_e32 v17, 0xffff0000, v13
	v_lshlrev_b32_e32 v20, 16, v12
	v_and_b32_e32 v21, 0xffff0000, v12
	s_waitcnt vmcnt(3)
	v_pk_mul_f32 v[12:13], v[108:109], v[16:17]
	s_waitcnt vmcnt(2)
	v_pk_fma_f32 v[12:13], v[114:115], v[110:111], v[12:13]
	s_waitcnt vmcnt(1)
	v_pk_fma_f32 v[12:13], v[104:105], v[20:21], v[12:13]
	v_add_u32_e32 v20, s54, v130
	s_waitcnt vmcnt(0)
	v_pk_add_f32 v[12:13], v[106:107], v[12:13]
	s_nop 0
	v_mul_f32_e32 v16, 0x3d372713, v12
	v_mul_f32_e32 v17, 0x3d372713, v13
	v_mul_f32_e32 v16, v12, v16
	v_mul_f32_e32 v17, v13, v17
	v_fma_f32 v16, v12, v16, v12
	v_fma_f32 v17, v13, v17, v13
	v_mul_f32_e32 v16, 0x3f4c422a, v16
	v_mul_f32_e32 v17, 0x3f4c422a, v17
	v_add_f32_e32 v16, v16, v16
	v_add_f32_e32 v17, v17, v17
	v_mul_f32_e32 v16, 0x3fb8aa3b, v16
	v_mul_f32_e32 v17, 0x3fb8aa3b, v17
	v_exp_f32_e32 v16, v16
	v_exp_f32_e32 v17, v17
	v_pk_mul_f32 v[12:13], v[12:13], 0.5 op_sel_hi:[1,0]
	v_add_f32_e32 v16, 1.0, v16
	v_add_f32_e32 v17, 1.0, v17
	v_rcp_f32_e32 v16, v16
	v_rcp_f32_e32 v17, v17
	s_nop 0
	v_pk_fma_f32 v[16:17], v[16:17], -2.0, 1.0 op_sel_hi:[1,0,0]
	s_nop 0
	v_pk_add_f32 v[16:17], v[16:17], 1.0 op_sel_hi:[1,0]
	s_nop 0
	v_pk_mul_f32 v[12:13], v[12:13], v[16:17]
	v_mov_b32_e32 v16, v14
	v_mov_b32_e32 v17, v18
	v_pk_mul_f32 v[12:13], v[16:17], v[12:13]
	s_nop 0
	v_cvt_pk_bf16_f32 v14, v12, v13
	v_add_u32_e32 v12, 0xa2, v20
	v_mad_i64_i32 v[12:13], s[0:1], v12, s87, v[98:99]
	global_store_dword v[12:13], v14, off
.LBB0_1242:
	s_or_b64 exec, exec, s[60:61]
	s_movk_i32 s0, 0xff5d
	s_movk_i32 s53, 0x5c
	v_cmp_lt_i32_e64 s[0:1], s0, v130
	v_cmp_gt_i32_e32 vcc, s53, v130
	s_or_b64 s[60:61], s[0:1], s[56:57]
	s_or_b64 s[62:63], vcc, s[58:59]
	s_and_b64 s[62:63], s[60:61], s[62:63]
	s_and_saveexec_b64 s[60:61], s[62:63]
	s_cbranch_execz .LBB0_1248
	v_mov_b32_e32 v12, 0
	v_mov_b32_e32 v13, 0
	s_and_saveexec_b64 s[62:63], s[0:1]
	v_add3_u32 v13, v158, v156, s92
	ds_read_b32 v13, v13
	s_or_b64 exec, exec, s[62:63]
	s_and_saveexec_b64 s[0:1], vcc
	v_lshl_add_u32 v12, v155, 1, v158
	ds_read_b32 v12, v12 offset:260
	s_or_b64 exec, exec, s[0:1]
	s_waitcnt lgkmcnt(0)
	v_lshlrev_b32_e32 v16, 16, v13
	v_and_b32_e32 v17, 0xffff0000, v13
	v_lshlrev_b32_e32 v20, 16, v12
	v_and_b32_e32 v21, 0xffff0000, v12
	s_waitcnt vmcnt(3)
	v_pk_mul_f32 v[12:13], v[108:109], v[16:17]
	v_mov_b32_e32 v18, v15
	s_waitcnt vmcnt(2)
	v_pk_fma_f32 v[12:13], v[22:23], v[110:111], v[12:13]
	s_waitcnt vmcnt(1)
	v_pk_fma_f32 v[12:13], v[104:105], v[20:21], v[12:13]
	s_waitcnt vmcnt(0)
	v_pk_add_f32 v[12:13], v[106:107], v[12:13]
	s_nop 0
	v_mul_f32_e32 v14, 0x3d372713, v12
	v_mul_f32_e32 v14, v12, v14
	v_mul_f32_e32 v16, 0x3d372713, v13
	v_fma_f32 v14, v12, v14, v12
	v_mul_f32_e32 v16, v13, v16
	v_mul_f32_e32 v14, 0x3f4c422a, v14
	v_fma_f32 v16, v13, v16, v13
	v_mul_f32_e32 v16, 0x3f4c422a, v16
	v_add_f32_e32 v14, v14, v14
	v_mul_f32_e32 v14, 0x3fb8aa3b, v14
	v_add_f32_e32 v16, v16, v16
	v_exp_f32_e32 v14, v14
	v_mul_f32_e32 v16, 0x3fb8aa3b, v16
	v_exp_f32_e32 v17, v16
	v_pk_mul_f32 v[12:13], v[12:13], 0.5 op_sel_hi:[1,0]
	v_add_f32_e32 v14, 1.0, v14
	v_rcp_f32_e32 v16, v14
	v_add_f32_e32 v14, 1.0, v17
	v_rcp_f32_e32 v17, v14
	v_add_u32_e32 v14, s54, v130
	v_pk_fma_f32 v[16:17], v[16:17], -2.0, 1.0 op_sel_hi:[1,0,0]
	s_nop 0
	v_pk_add_f32 v[16:17], v[16:17], 1.0 op_sel_hi:[1,0]
	s_nop 0
	v_pk_mul_f32 v[12:13], v[12:13], v[16:17]
	s_nop 0
	v_pk_mul_f32 v[12:13], v[18:19], v[12:13]
	s_nop 0
	v_cvt_pk_bf16_f32 v15, v12, v13
	v_add_u32_e32 v12, 0xa3, v14
	v_mad_i64_i32 v[12:13], s[0:1], v12, s87, v[98:99]
	global_store_dword v[12:13], v15, off
; __device__ __forceinline__ float bflo(unsigned u) { return __uint_as_float(u << 16); }
; __device__ __forceinline__ float bfhi(unsigned u) { return __uint_as_float(u & 0xffff0000u); }
; __device__ __forceinline__ float tanhf_(float x) { return 1.f - 2.f * __builtin_amdgcn_rcpf(1.f + __expf(2.f * x)); }
; __device__ __forceinline__ void phase_gemm5(const Params& p, int wid_s, char* shm) {
;     ...
;           for (int j = 0; j < 4; ++j) {
;             int r = ai * 128 + rbase + m * 16 + j;
;             bool doit = (r >= 1 || seq_first) && (r <= 254 || seq_last);
;             if (doit) {
;               unsigned gp = (r >= 1) ? *(const unsigned*)(gs_ + (r - 1) * 130 + cl) : 0u;
;               unsigned gn = (r <= 254) ? *(const unsigned*)(gs_ + (r + 1) * 130 + cl) : 0u;
;               float u0 = cw0.x * bflo(gp) + cw1.x * acc[ai][0][m][0][j] + cw2.x * bflo(gn) + cbv.x;
;               float u1 = cw0.y * bfhi(gp) + cw1.y * acc[ai][0][m][1][j] + cw2.y * bfhi(gn) + cbv.y;
;               float i0 = 0.7978845608028654f * (u0 + 0.044715f * u0 * u0 * u0);
;               float i1 = 0.7978845608028654f * (u1 + 0.044715f * u1 * u1 * u1);
;               float g0 = 0.5f * u0 * (1.f + tanhf_(i0));
;               float g1 = 0.5f * u1 * (1.f + tanhf_(i1));
;               *(unsigned*)(ACT + (size_t)(brow + r) * 5504 + f) = pack2(g0 * acc[ai][1][m][0][j], g1 * acc[ai][1][m][1][j]);
;             }
.LBB0_1248:
	s_or_b64 exec, exec, s[60:61]
	v_cmp_lt_i32_e64 s[0:1], s88, v130
	v_cmp_gt_i32_e32 vcc, s50, v130
	s_or_b64 s[60:61], s[0:1], s[56:57]
	s_or_b64 s[62:63], vcc, s[58:59]
	s_and_b64 s[62:63], s[60:61], s[62:63]
	s_and_saveexec_b64 s[60:61], s[62:63]
	s_cbranch_execz .LBB0_1254
	v_mov_b32_e32 v12, 0
	v_mov_b32_e32 v13, 0
	s_and_saveexec_b64 s[62:63], s[0:1]
	v_add3_u32 v13, v157, v156, s92
	ds_read_b32 v13, v13
	s_or_b64 exec, exec, s[62:63]
	s_and_saveexec_b64 s[0:1], vcc
	v_lshl_add_u32 v12, v155, 1, v157
	ds_read_b32 v12, v12 offset:260
	s_or_b64 exec, exec, s[0:1]
	s_waitcnt lgkmcnt(0)
	v_lshlrev_b32_e32 v14, 16, v13
	v_and_b32_e32 v15, 0xffff0000, v13
	v_lshlrev_b32_e32 v16, 16, v12
	v_and_b32_e32 v17, 0xffff0000, v12
	s_waitcnt vmcnt(3)
	v_pk_mul_f32 v[12:13], v[108:109], v[14:15]
	s_waitcnt vmcnt(2)
	v_pk_fma_f32 v[12:13], v[112:113], v[110:111], v[12:13]
	s_waitcnt vmcnt(1)
	v_pk_fma_f32 v[12:13], v[104:105], v[16:17], v[12:13]
	v_add_u32_e32 v16, s54, v130
	s_waitcnt vmcnt(0)
	v_pk_add_f32 v[12:13], v[106:107], v[12:13]
	s_nop 0
	v_mul_f32_e32 v14, 0x3d372713, v12
	v_mul_f32_e32 v15, 0x3d372713, v13
	v_mul_f32_e32 v14, v12, v14
	v_mul_f32_e32 v15, v13, v15
	v_fma_f32 v14, v12, v14, v12
	v_fma_f32 v15, v13, v15, v13
	v_mul_f32_e32 v14, 0x3f4c422a, v14
	v_mul_f32_e32 v15, 0x3f4c422a, v15
	v_add_f32_e32 v14, v14, v14
	v_add_f32_e32 v15, v15, v15
	v_mul_f32_e32 v14, 0x3fb8aa3b, v14
	v_mul_f32_e32 v15, 0x3fb8aa3b, v15
	v_exp_f32_e32 v14, v14
	v_exp_f32_e32 v15, v15
	v_pk_mul_f32 v[12:13], v[12:13], 0.5 op_sel_hi:[1,0]
	v_add_f32_e32 v14, 1.0, v14
	v_add_f32_e32 v15, 1.0, v15
	v_rcp_f32_e32 v14, v14
	v_rcp_f32_e32 v15, v15
	s_nop 0
	v_pk_fma_f32 v[14:15], v[14:15], -2.0, 1.0 op_sel_hi:[1,0,0]
	s_nop 0
	v_pk_add_f32 v[14:15], v[14:15], 1.0 op_sel_hi:[1,0]
	s_nop 0
	v_pk_mul_f32 v[12:13], v[12:13], v[14:15]
	v_mov_b32_e32 v14, v0
	v_mov_b32_e32 v15, v4
	v_pk_mul_f32 v[12:13], v[14:15], v[12:13]
	v_add_u32_e32 v4, 0xb0, v16
	v_cvt_pk_bf16_f32 v0, v12, v13
	v_mad_i64_i32 v[12:13], s[0:1], v4, s87, v[98:99]
	global_store_dword v[12:13], v0, off
.LBB0_1254:
	s_or_b64 exec, exec, s[60:61]
	v_cmp_lt_i32_e64 s[0:1], s89, v130
	v_cmp_gt_i32_e32 vcc, s51, v130
	s_or_b64 s[60:61], s[0:1], s[56:57]
	s_or_b64 s[62:63], vcc, s[58:59]
	s_and_b64 s[62:63], s[60:61], s[62:63]
	s_and_saveexec_b64 s[60:61], s[62:63]
	s_cbranch_execz .LBB0_1260
	v_mov_b32_e32 v0, 0
	v_mov_b32_e32 v4, 0
	s_and_saveexec_b64 s[62:63], s[0:1]
	v_add3_u32 v4, v145, v156, s92
	ds_read_b32 v4, v4
	s_or_b64 exec, exec, s[62:63]
	s_and_saveexec_b64 s[0:1], vcc
	v_lshl_add_u32 v0, v155, 1, v145
	ds_read_b32 v0, v0 offset:260
	s_or_b64 exec, exec, s[0:1]
	s_waitcnt lgkmcnt(0)
	v_lshlrev_b32_e32 v12, 16, v4
	v_and_b32_e32 v13, 0xffff0000, v4
	s_waitcnt vmcnt(3)
	v_pk_mul_f32 v[12:13], v[108:109], v[12:13]
	v_lshlrev_b32_e32 v14, 16, v0
	v_and_b32_e32 v15, 0xffff0000, v0
	s_waitcnt vmcnt(2)
	v_pk_fma_f32 v[8:9], v[8:9], v[110:111], v[12:13]
	s_waitcnt vmcnt(1)
	v_pk_fma_f32 v[8:9], v[104:105], v[14:15], v[8:9]
	v_add_u32_e32 v14, s54, v130
	s_waitcnt vmcnt(0)
	v_pk_add_f32 v[8:9], v[106:107], v[8:9]
	s_nop 0
	v_mul_f32_e32 v0, 0x3d372713, v8
	v_mul_f32_e32 v0, v8, v0
	v_mul_f32_e32 v4, 0x3d372713, v9
	v_fma_f32 v0, v8, v0, v8
	v_mul_f32_e32 v4, v9, v4
	v_mul_f32_e32 v0, 0x3f4c422a, v0
	v_fma_f32 v4, v9, v4, v9
	v_mul_f32_e32 v4, 0x3f4c422a, v4
	v_add_f32_e32 v0, v0, v0
	v_mul_f32_e32 v0, 0x3fb8aa3b, v0
	v_add_f32_e32 v4, v4, v4
	v_exp_f32_e32 v0, v0
	v_mul_f32_e32 v4, 0x3fb8aa3b, v4
	v_exp_f32_e32 v4, v4
	v_pk_mul_f32 v[8:9], v[8:9], 0.5 op_sel_hi:[1,0]
	v_add_f32_e32 v0, 1.0, v0
	v_rcp_f32_e32 v12, v0
	v_add_f32_e32 v0, 1.0, v4
	v_rcp_f32_e32 v13, v0
	v_mov_b32_e32 v4, v1
	v_pk_fma_f32 v[12:13], v[12:13], -2.0, 1.0 op_sel_hi:[1,0,0]
	s_nop 0
	v_pk_add_f32 v[12:13], v[12:13], 1.0 op_sel_hi:[1,0]
	s_nop 0
	v_pk_mul_f32 v[8:9], v[8:9], v[12:13]
	s_nop 0
	v_pk_mul_f32 v[0:1], v[4:5], v[8:9]
	s_nop 0
	v_cvt_pk_bf16_f32 v4, v0, v1
	v_add_u32_e32 v0, 0xb1, v14
	v_mad_i64_i32 v[0:1], s[0:1], v0, s87, v[98:99]
	global_store_dword v[0:1], v4, off
.LBB0_1260:
	s_or_b64 exec, exec, s[60:61]
	s_movk_i32 s0, 0xff4e
	v_cmp_lt_i32_e64 s[0:1], s0, v130
	v_cmp_gt_i32_e32 vcc, s96, v130
	s_or_b64 s[60:61], s[0:1], s[56:57]
	s_or_b64 s[62:63], vcc, s[58:59]
	s_and_b64 s[62:63], s[60:61], s[62:63]
	s_and_saveexec_b64 s[60:61], s[62:63]
	s_cbranch_execz .LBB0_1266
	v_mov_b32_e32 v0, 0
	v_mov_b32_e32 v1, 0
	s_and_saveexec_b64 s[62:63], s[0:1]
	v_add3_u32 v1, v131, v156, s92
	ds_read_b32 v1, v1
	s_or_b64 exec, exec, s[62:63]
	s_and_saveexec_b64 s[0:1], vcc
	v_lshl_add_u32 v0, v155, 1, v131
	ds_read_b32 v0, v0 offset:260
	s_or_b64 exec, exec, s[0:1]
	s_waitcnt lgkmcnt(0)
	v_lshlrev_b32_e32 v4, 16, v1
	v_and_b32_e32 v5, 0xffff0000, v1
	v_lshlrev_b32_e32 v8, 16, v0
	v_and_b32_e32 v9, 0xffff0000, v0
	s_waitcnt vmcnt(3)
	v_pk_mul_f32 v[0:1], v[108:109], v[4:5]
	s_waitcnt vmcnt(2)
	v_pk_fma_f32 v[0:1], v[102:103], v[110:111], v[0:1]
	s_waitcnt vmcnt(1)
	v_pk_fma_f32 v[0:1], v[104:105], v[8:9], v[0:1]
	s_waitcnt vmcnt(0)
	v_pk_add_f32 v[0:1], v[106:107], v[0:1]
	s_nop 0
	v_mul_f32_e32 v4, 0x3d372713, v0
	v_mul_f32_e32 v5, 0x3d372713, v1
	v_mul_f32_e32 v4, v0, v4
	v_mul_f32_e32 v5, v1, v5
	v_fma_f32 v4, v0, v4, v0
	v_fma_f32 v5, v1, v5, v1
	v_mul_f32_e32 v4, 0x3f4c422a, v4
	v_mul_f32_e32 v5, 0x3f4c422a, v5
	v_add_f32_e32 v4, v4, v4
	v_add_f32_e32 v5, v5, v5
	v_mul_f32_e32 v4, 0x3fb8aa3b, v4
	v_mul_f32_e32 v5, 0x3fb8aa3b, v5
	v_exp_f32_e32 v4, v4
	v_exp_f32_e32 v5, v5
	v_pk_mul_f32 v[0:1], v[0:1], 0.5 op_sel_hi:[1,0]
	v_add_f32_e32 v4, 1.0, v4
	v_add_f32_e32 v5, 1.0, v5
	v_rcp_f32_e32 v4, v4
	v_rcp_f32_e32 v5, v5
	s_nop 0
	v_pk_fma_f32 v[4:5], v[4:5], -2.0, 1.0 op_sel_hi:[1,0,0]
	s_nop 0
	v_pk_add_f32 v[4:5], v[4:5], 1.0 op_sel_hi:[1,0]
	s_nop 0
	v_pk_mul_f32 v[0:1], v[0:1], v[4:5]
	v_mov_b32_e32 v4, v2
	v_mov_b32_e32 v5, v6
	v_pk_mul_f32 v[0:1], v[4:5], v[0:1]
	s_nop 0
	v_cvt_pk_bf16_f32 v2, v0, v1
	v_add_u32_e32 v0, s54, v100
	v_mad_i64_i32 v[0:1], s[0:1], v0, s87, v[98:99]
	global_store_dword v[0:1], v2, off
